# DSA unit of a CU = its own indexer unit (scores self-produced): grid barrier between indexer/band and DSA phases removed
# speedup vs baseline: 1.0112x; 1.0112x over previous
; #define LAS __attribute__((address_space(3)))
; __device__ __forceinline__ unsigned xb_ld(unsigned* p)              { return __hip_atomic_load(p, __ATOMIC_RELAXED, __HIP_MEMORY_SCOPE_AGENT); }
; __device__ __forceinline__ unsigned xb_add(unsigned* p, unsigned v) { return __hip_atomic_fetch_add(p, v, __ATOMIC_RELAXED, __HIP_MEMORY_SCOPE_AGENT); }
; __device__ __forceinline__ unsigned xb_xcc_id() { return (unsigned)__builtin_amdgcn_s_getreg((3 << 11) | 20) & 0xFu; }
; __device__ __forceinline__ XcdBarrier xcd_barrier_post(unsigned* bar, volatile LAS unsigned* st) {
;     XcdBarrier b; b.bar = bar; b.x = xb_xcc_id(); b.st = st;
;     if (threadIdx.x == 0) (void)xb_add(&bar[XB_XCNT(b.x)], 1u);
;     return b;
; }
; __device__ __forceinline__ void xcd_barrier_complete(unsigned* bar, unsigned x, unsigned& nloc, unsigned& nx) {
;     const unsigned G = gridDim.x * gridDim.y * gridDim.z;
;     unsigned sum, cnt, mine, sp = 0u;
;     for (;;) {
;         sum = 0u; cnt = 0u; mine = 0u;
; #pragma unroll
;         for (unsigned j = 0; j < 16; ++j) { const unsigned c = xb_ld(&bar[XB_XCNT(j)]); sum += c; cnt += (c > 0u) ? 1u : 0u; mine = (j == x) ? c : mine; }
;         if (sum == G) break;
;         __builtin_amdgcn_s_sleep(1);
;         if ((++sp & 255u) == 0u) { if (xb_ld(&bar[XB_TMO])) break; if (sp > XB_SPIN_CAP) { atomicAdd(&bar[XB_TMO], 1u); break; } }
;     }
;     nloc = mine > 0u ? mine : 1u; nx = cnt > 0u ? cnt : 1u;
; }
; __global__ void __launch_bounds__(512, 2) k_mega(MegaArgs a) {
;     extern __shared__ __attribute__((aligned(16))) unsigned char dyn_lds[];
;     LAS unsigned char* lds = (LAS unsigned char*)dyn_lds;
;     volatile LAS unsigned* MISC = (volatile LAS unsigned*)(lds + MISC_OFF);
;     const int tid = threadIdx.x, lane_k = tid & 63, wave_k = __builtin_amdgcn_readfirstlane(tid >> 6);
;     const int ngw = gridDim.x * 8;
;     unsigned char* const ws_k = a.ws;
;     for (int u = tid; u < (LDS_BYTES - LDSCTL_OFF) / 4; u += 512) ((LAS unsigned*)(lds + LDSCTL_OFF))[u] = 0u;
;     __syncthreads();
;     XcdBarrier bar = xcd_barrier_post((unsigned*)(ws_k + WS_CTL) + CW_BAR, MISC + 8);
;     const int lo = a.st_lo, hi = a.st_hi; bool prev = false;
.LBB11_353:
	s_nop 0
	v_readlane_b32 s36, v249, 17
	v_readlane_b32 s50, v249, 31
	v_readlane_b32 s51, v249, 32
	s_add_u32 s2, s50, 0x4200
	s_addc_u32 s3, s51, 0
	v_readlane_b32 s37, v249, 18
	v_readlane_b32 s38, v249, 19
	v_readlane_b32 s39, v249, 20
	v_readlane_b32 s40, v249, 21
	v_readlane_b32 s41, v249, 22
	v_readlane_b32 s42, v249, 23
	v_readlane_b32 s43, v249, 24
	v_readlane_b32 s44, v249, 25
	v_readlane_b32 s45, v249, 26
	v_readlane_b32 s46, v249, 27
	v_readlane_b32 s47, v249, 28
	v_readlane_b32 s48, v249, 29
	v_readlane_b32 s49, v249, 30
	v_writelane_b32 v249, s2, 43
	s_movk_i32 s7, 0xb1
	v_mbcnt_lo_u32_b32 v1, -1, 0
	v_writelane_b32 v249, s3, 44
	s_add_u32 s2, s50, 0x4400
	s_addc_u32 s3, s51, 0
	v_writelane_b32 v249, s2, 45
	v_mov_b32_e32 v190, -1
	s_waitcnt vmcnt(0)
	v_mov_b32_e32 v3, 0
	v_writelane_b32 v249, s3, 46
	s_add_u32 s2, s50, 0x4500
	s_addc_u32 s3, s51, 0
	v_writelane_b32 v249, s2, 47
	v_mov_b32_e32 v209, 1
	v_mov_b32_e32 v210, 0x260
	v_writelane_b32 v249, s3, 48
	s_add_u32 s2, s50, 0x4600
	s_addc_u32 s3, s51, 0
	v_writelane_b32 v249, s2, 49
	v_mov_b32_e32 v182, 0x3c2936c6
	v_mov_b32_e32 v211, 0x3727c5ac
	v_writelane_b32 v249, s3, 50
	s_add_u32 s2, s50, 0x4700
	s_addc_u32 s3, s51, 0
	v_writelane_b32 v249, s2, 51
	v_mov_b32_e32 v213, 0x3f317218
	v_mov_b32_e32 v214, 0x3fb8aa3b
	v_writelane_b32 v249, s3, 52
	s_add_u32 s2, s50, 0x4800
	s_addc_u32 s3, s51, 0
	v_writelane_b32 v249, s2, 53
	v_mbcnt_hi_u32_b32 v215, -1, v1
	v_mov_b32_e32 v216, 0xff800000
	v_writelane_b32 v249, s3, 54
	s_add_u32 s2, s50, 0x4900
	s_addc_u32 s3, s51, 0
	v_writelane_b32 v249, s2, 55
	v_mov_b64_e32 v[188:189], 0x58000
	v_mov_b32_e32 v191, v190
	v_writelane_b32 v249, s3, 56
	s_add_u32 s2, s50, 0x4a00
	s_addc_u32 s3, s51, 0
	v_writelane_b32 v249, s2, 57
	v_mov_b64_e32 v[192:193], 0x100
	v_mov_b64_e32 v[194:195], 0xff
	v_writelane_b32 v249, s3, 58
	s_add_u32 s2, s50, 0x4b00
	s_addc_u32 s3, s51, 0
	v_writelane_b32 v249, s2, 59
	v_mov_b32_e32 v219, 0x7fc00000
	s_nop 0
	v_writelane_b32 v249, s3, 60
	s_add_u32 s2, s50, 0x4c00
	s_addc_u32 s3, s51, 0
	v_writelane_b32 v249, s2, 61
	s_nop 1
	v_writelane_b32 v249, s3, 62
	s_add_u32 s2, s50, 0x4d00
	s_addc_u32 s3, s51, 0
	v_writelane_b32 v249, s2, 63
	s_nop 0
	v_readlane_b32 s12, v249, 0
	s_lshr_b32 s100, s12, 2
	s_and_b32 s100, s100, 0x3e
	s_and_b32 s101, s12, 1
	s_or_b32 s100, s100, s101
	s_and_b32 s101, s12, 6
	s_lshl_b32 s101, s101, 4
	s_or_b32 s101, s101, s100
	s_cmp_lt_u32 s100, 32
	s_cselect_b32 s101, s101, 0xff
	v_writelane_b32 v255, s101, 9
	s_and_b32 s101, s12, 6
	s_lshl_b32 s101, s101, 5
	s_or_b32 s100, s100, s101
	v_writelane_b32 v255, s100, 8
	s_nop 1
	v_readlane_b32 s101, v255, 9
	v_writelane_b32 v250, s3, 0
	s_add_u32 s2, s50, 0x4e00
	s_addc_u32 s3, s51, 0
	v_writelane_b32 v250, s2, 1
	v_readlane_b32 s13, v249, 37
	s_nop 0
	v_writelane_b32 v250, s3, 2
	s_add_u32 s2, s50, 0x4f00
	s_addc_u32 s3, s51, 0
	v_writelane_b32 v250, s2, 3
	s_nop 1
	v_writelane_b32 v250, s3, 4
	s_add_u32 s2, s50, 0x5000
	s_addc_u32 s3, s51, 0
	v_writelane_b32 v250, s2, 5
	s_nop 1
	v_writelane_b32 v250, s3, 6
	s_add_u32 s2, s50, 0x5100
	s_addc_u32 s3, s51, 0
	v_writelane_b32 v250, s2, 7
	s_nop 1
	v_writelane_b32 v250, s3, 8
	s_add_u32 s2, s50, 0x5200
	s_addc_u32 s3, s51, 0
	v_writelane_b32 v250, s2, 9
	s_nop 1
	v_writelane_b32 v250, s3, 10
	s_add_u32 s2, s50, 0x5300
	s_addc_u32 s3, s51, 0
	v_writelane_b32 v250, s2, 11
	s_cmp_eq_u32 s33, 15
	s_nop 0
	v_writelane_b32 v250, s3, 12
	s_cselect_b64 s[2:3], -1, 0
	v_writelane_b32 v250, s2, 13
	s_cmp_eq_u32 s33, 14
	s_nop 0
	v_writelane_b32 v250, s3, 14
	s_cselect_b64 s[2:3], -1, 0
	v_writelane_b32 v250, s2, 15
	s_cmp_eq_u32 s33, 13
	s_nop 0
	v_writelane_b32 v250, s3, 16
	s_cselect_b64 s[2:3], -1, 0
	v_writelane_b32 v250, s2, 17
	s_cmp_eq_u32 s33, 12
	s_nop 0
	v_writelane_b32 v250, s3, 18
	s_cselect_b64 s[2:3], -1, 0
	v_writelane_b32 v250, s2, 19
	s_cmp_eq_u32 s33, 11
	s_nop 0
	v_writelane_b32 v250, s3, 20
	s_cselect_b64 s[2:3], -1, 0
	v_writelane_b32 v250, s2, 21
	s_cmp_eq_u32 s33, 10
	s_nop 0
	v_writelane_b32 v250, s3, 22
	s_cselect_b64 s[2:3], -1, 0
	v_writelane_b32 v250, s2, 23
	s_cmp_eq_u32 s33, 9
	s_nop 0
	v_writelane_b32 v250, s3, 24
	s_cselect_b64 s[2:3], -1, 0
	v_writelane_b32 v250, s2, 25
	s_cmp_eq_u32 s33, 8
	s_nop 0
	v_writelane_b32 v250, s3, 26
	s_cselect_b64 s[2:3], -1, 0
	v_writelane_b32 v250, s2, 27
	s_cmp_eq_u32 s33, 7
	s_nop 0
	v_writelane_b32 v250, s3, 28
	s_cselect_b64 s[2:3], -1, 0
	v_writelane_b32 v250, s2, 29
	s_cmp_eq_u32 s33, 6
	s_nop 0
	v_writelane_b32 v250, s3, 30
	s_cselect_b64 s[2:3], -1, 0
	v_writelane_b32 v250, s2, 31
	s_cmp_eq_u32 s33, 5
	s_nop 0
	v_writelane_b32 v250, s3, 32
	s_cselect_b64 s[2:3], -1, 0
	v_writelane_b32 v250, s2, 33
	s_cmp_eq_u32 s33, 4
	s_nop 0
	v_writelane_b32 v250, s3, 34
	s_cselect_b64 s[2:3], -1, 0
	v_writelane_b32 v250, s2, 35
	s_cmp_eq_u32 s33, 3
	s_nop 0
	v_writelane_b32 v250, s3, 36
	s_cselect_b64 s[2:3], -1, 0
	v_writelane_b32 v250, s2, 37
	s_cmp_eq_u32 s33, 2
	s_nop 0
	v_writelane_b32 v250, s3, 38
	s_cselect_b64 s[2:3], -1, 0
	v_writelane_b32 v250, s2, 39
	s_cmp_eq_u32 s33, 1
	s_nop 0
	v_writelane_b32 v250, s3, 40
	s_cselect_b64 s[2:3], -1, 0
	v_writelane_b32 v250, s2, 41
	s_cmp_eq_u32 s33, 0
	s_nop 0
	v_writelane_b32 v250, s3, 42
	s_cselect_b64 s[2:3], -1, 0
	v_writelane_b32 v250, s2, 43
	s_nop 1
	v_writelane_b32 v250, s3, 44
	s_lshl_b32 s2, s33, 8
	s_add_u32 s0, s0, s2
	s_addc_u32 s1, s1, 0
	s_add_u32 s2, s0, 0x1400
	s_addc_u32 s3, s1, 0
	v_writelane_b32 v250, s2, 45
	s_add_u32 s0, s0, 0x2400
	s_addc_u32 s1, s1, 0
	v_writelane_b32 v250, s3, 46
	v_writelane_b32 v250, s0, 47
	s_nop 1
	v_writelane_b32 v250, s1, 48
; #define LAS __attribute__((address_space(3)))
; DEVI void cross_phase(LAS unsigned char* lds, const bf16_t* XQ, const bf16_t* KVX, bf16_t* XO, int layer) {
;     const int wid = otid() >> 6;
;     for (int u = blockIdx.x; u < NB * 4 * 8; u += gridDim.x) {
;         const int qb = u & 7, h = (u >> 3) & 3, b = u >> 5; const int m0 = b * SEQ + qb * 256 + wid * 32;
;         attn_unit<M_CROSS>(lds, XQ + (size_t)m0 * 512 + h * HD, 512, KVX + (size_t)(b * MEML) * 4096 + layer * 1024 + h * HD, KVX + (size_t)(b * MEML) * 4096 + layer * 1024 + 512 + h * HD, 4096,
;                            XO + (size_t)m0 * 512 + h * HD, 512, 0, 4, 1, 0, 1 << 30, 0);
;     }
; DEVI void convert_layer_range(const MegaArgs& a, int L, int t_lo, int t_hi, int w, int nw, LAS float* scr, int lane) {
;     unsigned char* ws = a.ws;
;     const int i = L >> 1; const bool even = !(L & 1);
;     const int n_mixin = (even ? EVP / 32 : ODD_COLS / 32) * (DM / 64);
;     const int c1 = 11264, c2 = c1 + 5632, c3 = c2 + n_mixin, c4 = c3 + 2048, c5 = c4 + 512, c6 = c5 + 512, c7 = c6 + 11264, total = c7 + 5632;
;     const int lo = (int)((long)total * t_lo / 10), hi = (int)((long)total * t_hi / 10);
;     for (int it = lo + w; it < hi; it += nw) {
;         const float* W; bf16_t* WT; int ldw, nsrc, K, mode, loc;
;         if (it < c1 || (it >= c6 && it < c7)) { const int j = it >= c6; loc = it - (j ? c6 : 0); W = a.in[4] + (size_t)(L * 2 + j) * DM * 2 * FFN; ldw = 2 * FFN; nsrc = 2 * FFN; K = DM; WT = (bf16_t*)(ws + WS_WF_FFN_IN + (L * 2 + j) * SZ_FFN_IN); mode = 1; }
;         else if (it < c2 || it >= c7) { const int j = it >= c7; loc = it - (j ? c7 : c1); W = a.in[5] + (size_t)(L * 2 + j) * FFN * DM; ldw = DM; nsrc = DM; K = FFN; WT = (bf16_t*)(ws + WS_W_FFN_OUT + (L * 2 + j) * SZ_FFN_OUT); mode = 0; }
;         else if (it < c3) { loc = it - c2; K = DM;
;             if (even) { W = a.in[9] + (size_t)i * DM * EVEN_COLS; ldw = EVEN_COLS; nsrc = EVEN_COLS; WT = (bf16_t*)(ws + WS_WF_EVEN_IN + i * SZ_EVEN_IN); mode = 2; }
;             else { W = a.in[12] + (size_t)i * DM * ODD_COLS; ldw = ODD_COLS; nsrc = ODD_COLS; WT = (bf16_t*)(ws + WS_W_ODD_IN + i * SZ_ODD_IN); mode = 0; } }
;         else if (it < c4) { loc = it - c3; W = (even ? a.in[10] : a.in[13]) + (size_t)i * DM * DM; ldw = DM; nsrc = DM; K = DM; WT = (bf16_t*)(ws + WS_W_MIX_OUT + L * SZ_MIX_OUT); mode = 0; }
	s_add_u32 s0, s50, 0x7400
	s_addc_u32 s1, s51, 0
	v_writelane_b32 v250, s0, 49
	s_nop 1
	v_writelane_b32 v250, s1, 50
	s_add_u32 s0, s50, 0x7500
	s_addc_u32 s1, s51, 0
	v_writelane_b32 v250, s0, 51
	s_cmp_lt_i32 s12, 64
	s_nop 0
	v_writelane_b32 v250, s1, 52
	s_cselect_b64 s[0:1], -1, 0
	v_writelane_b32 v250, s0, 53
	s_nop 1
	v_writelane_b32 v250, s1, 54
	s_ashr_i32 s0, s12, 31
	v_writelane_b32 v250, s0, 55
	s_lshr_b32 s0, s0, 29
	s_add_i32 s0, s12, s0
	s_ashr_i32 s2, s0, 3
	s_and_b32 s0, s0, -8
	s_sub_i32 s3, s12, s0
	s_lshl_b32 s6, s3, 3
	s_ashr_i32 s0, s13, 31
	s_cmpk_lg_i32 s13, 0x100
	v_writelane_b32 v250, s0, 56
	s_cselect_b64 s[0:1], -1, 0
	v_writelane_b32 v250, s0, 57
	s_cmpk_eq_i32 s13, 0x100
	s_nop 0
	v_writelane_b32 v250, s1, 58
	s_cselect_b64 s[0:1], -1, 0
	s_cmp_gt_u32 s12, 63
	s_cselect_b64 s[4:5], -1, 0
	s_and_b64 s[4:5], s[4:5], s[0:1]
	v_writelane_b32 v250, s4, 59
	s_lshl_b32 s14, s12, 3
	s_nop 0
	v_writelane_b32 v250, s5, 60
	s_add_i32 s4, s14, 0xfffffe00
	v_writelane_b32 v250, s4, 61
	s_add_u32 s4, s50, 0x16300000
	s_addc_u32 s5, s51, 0
	v_writelane_b32 v250, s4, 62
	s_nop 1
	v_writelane_b32 v250, s5, 63
	s_add_u32 s4, s50, 0x2a700000
	v_writelane_b32 v251, s4, 0
	s_addc_u32 s4, s51, 0
	v_writelane_b32 v251, s4, 1
	s_add_u32 s4, s50, 0x28f00000
	v_writelane_b32 v251, s4, 2
	s_addc_u32 s4, s51, 0
	v_writelane_b32 v251, s4, 3
	s_add_u32 s4, s50, 0x26f00000
	v_writelane_b32 v251, s4, 4
	s_addc_u32 s4, s51, 0
	v_writelane_b32 v251, s4, 5
	s_add_u32 s4, s50, 0x23f00000
	v_writelane_b32 v251, s4, 6
	s_addc_u32 s4, s51, 0
	v_writelane_b32 v251, s4, 7
	s_add_u32 s4, s50, 0x21300000
	v_writelane_b32 v251, s4, 8
	s_addc_u32 s4, s51, 0
	v_writelane_b32 v251, s4, 9
	s_add_u32 s4, s50, 0x300000
	s_addc_u32 s5, s51, 0
	v_writelane_b32 v251, s4, 10
	s_cmpk_lt_i32 s101, 0x80
	s_nop 0
	v_writelane_b32 v251, s5, 11
	s_cselect_b64 s[4:5], -1, 0
	v_writelane_b32 v251, s4, 12
	s_cmpk_lt_i32 s12, 0x300
	s_nop 0
	v_writelane_b32 v251, s5, 13
	s_cselect_b64 s[4:5], -1, 0
	v_writelane_b32 v251, s4, 14
	s_cmpk_lt_i32 s12, 0x100
	s_nop 0
	v_writelane_b32 v251, s5, 15
	s_cselect_b64 s[4:5], -1, 0
	v_writelane_b32 v251, s4, 16
	s_cmpk_lt_i32 s12, 0x2c0
	s_nop 0
	v_writelane_b32 v251, s5, 17
	s_cselect_b64 s[4:5], -1, 0
	v_writelane_b32 v251, s4, 18
	s_nop 1
	v_writelane_b32 v251, s5, 19
	s_lshl_b32 s4, s3, 5
	s_cmp_lt_i32 s3, 0
	s_mul_i32 s5, s3, 9
	s_cselect_b32 s5, s5, s6
	s_mul_i32 s6, s3, 33
	s_cselect_b32 s4, s6, s4
	s_movk_i32 s6, 0x59
	s_cselect_b32 s6, s6, 0x58
	s_mul_i32 s6, s6, s3
	s_cselect_b32 s8, s7, 0xb0
	s_movk_i32 s7, 0x61
	s_cselect_b32 s9, s7, 0x60
	s_add_i32 s6, s6, s2
	s_mul_hi_i32 s7, s6, 0x2e8ba2e9
	s_lshr_b32 s10, s7, 31
	s_ashr_i32 s7, s7, 5
	s_add_i32 s7, s7, s10
	s_mul_i32 s10, s7, 0xb0
	s_sub_i32 s6, s6, s10
	s_bfe_u32 s10, s6, 0x3001c
	s_add_i32 s10, s6, s10
	s_and_b32 s11, s10, 0xfff8
	s_sub_i32 s6, s6, s11
	s_lshl_b32 s7, s7, 3
	s_sext_i32_i16 s10, s10
	s_sext_i32_i16 s6, s6
	s_add_i32 s16, s7, s6
	s_ashr_i32 s6, s10, 3
	v_writelane_b32 v251, s6, 20
	s_lshr_b32 s6, s10, 3
	s_bfe_i64 s[6:7], s[6:7], 0x100000
	s_lshl_b64 s[6:7], s[6:7], 20
	v_writelane_b32 v251, s6, 21
	s_ashr_i32 s17, s16, 31
	s_nop 0
	v_writelane_b32 v251, s7, 22
	s_mov_b32 s6, s16
	v_writelane_b32 v251, s6, 23
	s_nop 1
	v_writelane_b32 v251, s7, 24
	s_lshl_b64 s[6:7], s[16:17], 20
	v_writelane_b32 v251, s6, 25
	s_cmpk_gt_u32 s12, 0xbf
	v_readlane_b32 s16, v249, 1
	v_writelane_b32 v251, s7, 26
	s_cselect_b64 s[6:7], -1, 0
	s_and_b64 s[6:7], s[6:7], s[0:1]
	v_writelane_b32 v251, s6, 27
	v_readlane_b32 s17, v249, 2
	v_readlane_b32 s31, v249, 16
	v_writelane_b32 v251, s7, 28
	s_add_i32 s6, s14, 0xfffffa00
	v_writelane_b32 v251, s6, 29
	s_cmpk_lt_i32 s12, 0x580
	s_mul_i32 s6, s8, s3
	s_cselect_b64 s[10:11], -1, 0
	s_add_i32 s6, s6, s2
	s_mul_hi_i32 s7, s6, 0x2e8ba2e9
	s_lshr_b32 s8, s7, 31
	s_ashr_i32 s7, s7, 6
	s_add_i32 s7, s7, s8
	s_mul_i32 s8, s7, 0x160
	s_sub_i32 s6, s6, s8
	s_bfe_u32 s8, s6, 0x3001c
	v_writelane_b32 v251, s10, 30
	s_add_i32 s8, s6, s8
	s_lshl_b32 s7, s7, 3
	v_writelane_b32 v251, s11, 31
	s_and_b32 s10, s8, 0xfff8
	s_sub_i32 s6, s6, s10
	s_sext_i32_i16 s8, s8
	s_sext_i32_i16 s6, s6
	s_add_i32 s10, s7, s6
	s_ashr_i32 s6, s8, 3
	v_writelane_b32 v251, s6, 32
	s_lshr_b32 s6, s8, 3
	s_bfe_i64 s[6:7], s[6:7], 0x100000
	s_lshl_b64 s[6:7], s[6:7], 20
	v_writelane_b32 v251, s6, 33
	s_ashr_i32 s11, s10, 31
	s_mul_i32 s3, s3, s9
	v_writelane_b32 v251, s7, 34
; #define LAS __attribute__((address_space(3)))
; DEVI int otid() { int t = threadIdx.x; asm volatile("" : "+v"(t)); return t; }
; DEVI void indexer_phase(LAS unsigned char* lds, const bf16_t* EV, float* SC) {
;     const int tid = otid(), wid = tid >> 6, lane = tid & 63, r32 = lane & 31, hi = lane >> 5;
;     LAS float* wl = (LAS float*)(lds + 66560);
;     for (int u = blockIdx.x; u < NB * 64; u += gridDim.x) {
;         const int g = u & 63, b = u >> 6, m0 = b * SEQ + 32 * g, nt = (g >> 1) + 1;
; DEVI void dsa_phase(LAS unsigned char* lds, const bf16_t* EV, const float* SC, bf16_t* O) {
;     const int tid = otid(), wid = tid >> 6, lane = tid & 63;
;     LAS u64* maskl = (LAS u64*)(lds + OFF_MASK);
;     for (int u = blockIdx.x; u < NB * 64; u += gridDim.x) {
;         const int g = 63 - (u & 63), b = u >> 6, t0 = 32 * g, m0 = b * SEQ + t0, c = g >> 1;
	s_mov_b32 s6, s10
	v_writelane_b32 v251, s6, 35
	s_mov_b32 s31, 0
	v_readlane_b32 s18, v249, 3
	v_writelane_b32 v251, s7, 36
	s_lshl_b64 s[6:7], s[10:11], 20
	v_writelane_b32 v251, s6, 37
	s_cmpk_gt_u32 s12, 0x7f
	v_readlane_b32 s19, v249, 4
	v_writelane_b32 v251, s7, 38
	s_cselect_b64 s[6:7], -1, 0
	s_and_b64 s[0:1], s[6:7], s[0:1]
	v_writelane_b32 v251, s0, 39
	v_readlane_b32 s20, v249, 5
	v_readlane_b32 s21, v249, 6
	v_writelane_b32 v251, s1, 40
	s_add_i32 s0, s14, 0xfffffc00
	v_writelane_b32 v251, s14, 41
	s_cmp_eq_u64 s[16:17], 0
	v_writelane_b32 v251, s0, 42
	s_cselect_b64 s[0:1], -1, 0
	v_writelane_b32 v251, s0, 43
	s_cmp_eq_u64 s[48:49], 0
	v_readlane_b32 s22, v249, 7
	v_writelane_b32 v251, s1, 44
	s_cselect_b64 s[0:1], -1, 0
	v_writelane_b32 v251, s0, 45
	s_add_i32 s3, s3, s2
	s_ashr_i32 s97, s96, 31
	v_writelane_b32 v251, s1, 46
	s_add_i32 s0, s5, s2
	s_ashr_i32 s1, s0, 31
	s_lshr_b32 s1, s1, 28
	s_add_i32 s1, s0, s1
	s_and_b32 s5, s1, 0xfff0
	s_sub_i32 s0, s0, s5
	s_bfe_i32 s5, s0, 0x80000
	s_bfe_u32 s5, s5, 0x3000c
	s_add_i32 s5, s0, s5
	s_and_b32 s6, s5, 0xf8
	s_sub_i32 s0, s0, s6
	s_mul_hi_i32 s6, s3, 0x2aaaaaab
	s_lshr_b32 s7, s6, 31
	s_ashr_i32 s6, s6, 5
	s_add_i32 s6, s6, s7
	s_mul_i32 s7, s6, 0xc0
	s_sub_i32 s3, s3, s7
	s_add_i32 s2, s4, s2
	s_bfe_u32 s7, s3, 0x3001c
	s_ashr_i32 s4, s2, 31
	s_add_i32 s7, s3, s7
	s_lshr_b32 s4, s4, 26
	s_and_b32 s8, s7, 0xfff8
	s_add_i32 s4, s2, s4
	s_sub_i32 s3, s3, s8
	s_and_b32 s8, s4, 0xffc0
	s_sub_i32 s2, s2, s8
	s_bfe_i32 s8, s2, 0x80000
	s_bfe_u32 s8, s8, 0x3000c
	s_add_i32 s8, s2, s8
	s_and_b32 s9, s8, 0xf8
	s_sub_i32 s2, s2, s9
	s_ashr_i32 s4, s4, 6
	s_lshl_b32 s4, s4, 3
	s_sext_i32_i8 s2, s2
	s_add_i32 s2, s4, s2
	v_writelane_b32 v251, s2, 47
	s_ashr_i32 s1, s1, 4
	s_bfe_i32 s2, s5, 0x80000
	s_lshl_b32 s1, s1, 3
	s_sext_i32_i16 s2, s2
	s_sext_i32_i8 s0, s0
	s_add_i32 s4, s1, s0
	s_ashr_i32 s0, s2, 3
	v_writelane_b32 v251, s0, 48
	s_lshr_b32 s0, s2, 3
	s_bfe_i64 s[0:1], s[0:1], 0x100000
	s_lshl_b64 s[0:1], s[0:1], 20
	v_writelane_b32 v251, s0, 49
	s_sext_i32_i16 s2, s3
	s_ashr_i32 s5, s4, 31
	v_writelane_b32 v251, s1, 50
	s_lshl_b32 s0, s6, 3
	s_sext_i32_i16 s1, s7
	s_add_i32 s2, s0, s2
	s_ashr_i32 s0, s1, 3
	v_writelane_b32 v251, s0, 51
	s_lshr_b32 s0, s1, 3
	s_bfe_i64 s[0:1], s[0:1], 0x100000
	s_lshl_b64 s[0:1], s[0:1], 20
	v_writelane_b32 v251, s0, 52
	s_ashr_i32 s3, s2, 31
	v_readlane_b32 s23, v249, 8
	v_writelane_b32 v251, s1, 53
	s_bfe_i32 s0, s8, 0x80000
	s_sext_i32_i16 s0, s0
	s_ashr_i32 s1, s0, 3
	s_lshr_b32 s0, s0, 3
	v_writelane_b32 v251, s1, 54
	s_bfe_i64 s[0:1], s[0:1], 0x100000
	v_writelane_b32 v251, s0, 55
	v_readlane_b32 s24, v249, 9
	v_readlane_b32 s25, v249, 10
	v_writelane_b32 v251, s1, 56
	s_lshl_b32 s0, s101, 4
	v_writelane_b32 v251, s0, 57
	s_lshl_b32 s0, s13, 4
	v_writelane_b32 v251, s0, 58
	s_lshl_b32 s0, s100, 5
	v_writelane_b32 v251, s0, 59
	s_lshl_b32 s0, s13, 5
	v_writelane_b32 v251, s0, 60
	s_xor_b32 s0, s100, 63
	v_writelane_b32 v251, s0, 61
	s_mov_b32 s100, 0
	s_mov_b32 s0, s4
	v_writelane_b32 v251, s0, 62
	v_readlane_b32 s26, v249, 11
	v_readlane_b32 s27, v249, 12
	v_writelane_b32 v251, s1, 63
	s_lshl_b64 s[0:1], s[4:5], 20
	v_writelane_b32 v252, s0, 0
	v_readlane_b32 s28, v249, 13
	v_readlane_b32 s29, v249, 14
	v_writelane_b32 v252, s1, 1
	s_mov_b32 s0, s2
	v_writelane_b32 v252, s0, 2
	v_readlane_b32 s30, v249, 15
	s_nop 0
	v_writelane_b32 v252, s1, 3
	s_lshl_b64 s[0:1], s[2:3], 20
	v_writelane_b32 v252, s0, 4
	s_nop 1
	v_writelane_b32 v252, s1, 5
	s_lshl_b64 s[0:1], s[96:97], 13
	v_writelane_b32 v252, s0, 6
	s_nop 1
	v_writelane_b32 v252, s1, 7
	s_add_u32 s0, s50, 0x47a00800
	s_addc_u32 s1, s51, 0
	v_writelane_b32 v252, s0, 8
	s_nop 1
	v_writelane_b32 v252, s1, 9
	s_add_i32 s0, 0, 0x20160
	v_writelane_b32 v252, s0, 10
	s_add_i32 s0, 0, 0x20164
	v_writelane_b32 v252, s0, 11
	s_add_i32 s0, 0, 0x12c00
	v_writelane_b32 v252, s0, 12
	s_add_i32 s0, 0, 0x10400
	v_writelane_b32 v252, s0, 13
	s_add_i32 s0, 0, 0x12afc
	v_writelane_b32 v252, s0, 14
	s_add_i32 s0, 0, 0x10800
	v_writelane_b32 v252, s0, 15
	s_mov_b32 s0, 0
	v_writelane_b32 v252, s0, 16
	s_mov_b64 s[0:1], 0
	v_writelane_b32 v252, s0, 17
	s_nop 1
	v_writelane_b32 v252, s1, 18
	s_mov_b32 s0, s96
	v_writelane_b32 v252, s0, 19
	s_nop 1
	v_writelane_b32 v252, s1, 20
	s_lshl_b64 s[0:1], s[96:97], 12
	v_writelane_b32 v252, s0, 21
	s_nop 1
	v_writelane_b32 v252, s1, 22
	s_mov_b32 s0, 0x3e0293ee
	s_branch .LBB11_358

; template <class Epi, class Sched, bool ALIGN_EPI = false, bool SP2 = false>
; __device__ __forceinline__ void gemm_phase(PG8_LAS unsigned char* lds, const Gemm g, const Sched& S, const Epi& E) {
;     int tid_ = threadIdx.x; asm volatile("" : "+v"(tid_));
;     const int tid = tid_, wid = __builtin_amdgcn_readfirstlane(tid >> 6), lane = tid & 63, wr = wid >> 2, wc = wid & 3, fr = lane & 15, fq = lane >> 4;
;     const int K = g.K, nt = K / BK;
;     unsigned voffA[2], voffB[2];
; #pragma unroll
;     for (int i = 0; i < 2; ++i) { int R, C; stage_rc(tid * 16 + i * 8192, R, C); const int Rb = Epi::PERM ? ((R & ~31) + perm32(R & 31)) : R;
;         voffA[i] = (unsigned)(R * K + C) * 2u; voffB[i] = (unsigned)(Rb * K + C) * 2u; }
;     const size_t kstep = (size_t)(BK * 2);
;     const size_t hstep = (size_t)HALF * K * 2;
;     const size_t tstep = 2 * hstep;
;     const unsigned ldsw = (unsigned)wid * 1024u;
;     const int aoff = lds_byte(wr * 64 + fr, fq * 8), boff = lds_byte(wc * 32 + fr, fq * 8);
;     ...
;     Unit cur, nxt; int ui = 0;
;     if (!S.next(0, cur)) return;
;     f32x4 acc[2][2][4][2];
; #pragma unroll
;     for (int a = 0; a < 2; ++a)
; #pragma unroll
;         for (int b = 0; b < 2; ++b)
; #pragma unroll
;             for (int m = 0; m < 4; ++m)
; #pragma unroll
;                 for (int n = 0; n < 2; ++n) acc[a][b][m][n] = (f32x4){0.f, 0.f, 0.f, 0.f};
;     bf16x8 At[4][2], B0[2][2], B1[2][2];
;     const char* cA = (const char*)g.A + (size_t)cur.pm * tstep; const char* cB = (const char*)g.Bt + (size_t)cur.pn * tstep;
;     S.a_ready(cur);
;     if constexpr (SP2) {
;         PG8_STAGE(PG8_SB(0, 0), cB, voffB); PG8_STAGE(PG8_SB(0, 1), cB + hstep, voffB); PG8_STAGE(PG8_SA(0, 0), cA, voffA); PG8_STAGE(PG8_SA(0, 1), cA + hstep, voffA);
;         if (wr == 1) PG8_BAR;
;         PG8_WAIT_V(2); PG8_BAR;
;         PG8_STAGE(PG8_SB(1, 0), cB + kstep, voffB); PG8_STAGE(PG8_SA(1, 0), cA + kstep, voffA); PG8_STAGE(PG8_SB(1, 1), cB + hstep + kstep, voffB);
;         PG8_WAIT_V(6); PG8_BAR;
;     } else {
;         PG8_STAGE(PG8_SB(0, 0), cB, voffB); PG8_STAGE(PG8_SA(0, 0), cA, voffA); PG8_STAGE(PG8_SB(0, 1), cB + hstep, voffB); PG8_STAGE(PG8_SA(0, 1), cA + hstep, voffA);
;         if (wr == 1) PG8_BAR;
;         PG8_WAIT_V(4); PG8_BAR;
; __device__ __forceinline__ void xcd_barrier(const XcdBarrier& b) {
;     asm volatile("s_waitcnt vmcnt(0)" ::: "memory");
.LBB11_446:
	s_or_b64 exec, exec, s[4:5]
	s_waitcnt lgkmcnt(0)
	s_barrier
	s_cmp_lg_u32 s100, 1
	s_cbranch_scc1 .Lsg_ffn
	v_readlane_b32 s101, v249, 0
	s_and_b32 s101, s101, 6
	s_lshl_b32 s101, s101, 8
	s_addk_i32 s101, 0x400
	v_readlane_b32 s100, v250, 49
	s_sub_u32 s100, s100, s101
	v_writelane_b32 v250, s100, 49
	s_nop 1
	v_readlane_b32 s100, v250, 50
	s_subb_u32 s100, s100, 0
	v_writelane_b32 v250, s100, 50
	s_nop 1
	v_readlane_b32 s100, v250, 51
	s_sub_u32 s100, s100, s101
	v_writelane_b32 v250, s100, 51
	s_nop 1
	v_readlane_b32 s100, v250, 52
	s_subb_u32 s100, s100, 0
	v_writelane_b32 v250, s100, 52
	s_nop 1
	v_readlane_b32 s100, v252, 11
	s_nop 3
	v_mov_b32_e32 v1, s100
	v_mov_b32_e32 v2, 8
	ds_write_b32 v1, v2
	s_waitcnt lgkmcnt(0)
	s_mov_b32 s100, 0
.Lsg_ffn:
.LBB11_447:
	v_readlane_b32 s6, v251, 30
	v_readlane_b32 s1, v249, 40
	s_mov_b64 s[4:5], 0
	v_and_b32_e32 v1, 63, v0
	v_mov_b32_e32 v14, v0
	v_readlane_b32 s7, v251, 31
	s_andn2_b64 vcc, exec, s[6:7]
	v_readfirstlane_b32 s6, v14
	s_cbranch_vccnz .LBB11_463
	v_lshlrev_b32_e32 v2, 4, v14
	v_add_u32_e32 v8, 0x2000, v2
	v_ashrrev_i32_e32 v9, 31, v8
	v_lshrrev_b32_e32 v9, 22, v9
	v_add_u32_e32 v9, v8, v9
	v_ashrrev_i32_e32 v15, 10, v9
	v_mul_i32_i24_e32 v9, 0x400, v15
	v_sub_u32_e32 v8, v8, v9
	v_lshrrev_b32_e32 v9, 4, v8
	v_bitop3_b32 v8, v9, v8, 32 bitop3:0x6c
	v_ashrrev_i32_e32 v9, 31, v8
	v_readlane_b32 s8, v249, 17
	v_lshrrev_b32_e32 v9, 26, v9
	v_mov_b64_e32 v[4:5], s[4:5]
	v_readlane_b32 s22, v249, 31
	v_readlane_b32 s23, v249, 32
	v_add_u32_e32 v9, v8, v9
	v_lshlrev_b32_e32 v12, 3, v15
	s_mul_i32 s30, s26, 0x2c00000
	v_lshl_add_u64 v[4:5], s[22:23], 0, v[4:5]
	s_mov_b64 s[4:5], 0x47a00000
	v_ashrrev_i32_e32 v16, 6, v9
	v_and_b32_e32 v12, -16, v12
	v_lshl_add_u64 v[10:11], v[4:5], 0, s[4:5]
	v_lshl_add_u64 v[6:7], v[4:5], 0, s[30:31]
	s_mov_b64 s[4:5], 0x300000
	v_add_u32_e32 v12, v16, v12
	v_lshl_add_u64 v[6:7], v[6:7], 0, s[4:5]
	v_and_b32_e32 v13, 3, v16
	s_mov_b32 s4, 0xfffe0
	v_lshrrev_b32_e32 v17, 2, v12
	v_lshlrev_b32_e32 v18, 1, v12
	v_and_b32_e32 v9, 0xc0, v9
	v_and_or_b32 v13, v12, s4, v13
	v_and_b32_e32 v17, 4, v17
	v_and_b32_e32 v18, 24, v18
	v_sub_u32_e32 v8, v8, v9
	v_or3_b32 v13, v13, v17, v18
	v_lshlrev_b32_e32 v17, 5, v15
	v_ashrrev_i16_sdwa v8, v209, sext(v8) dst_sel:DWORD dst_unused:UNUSED_PAD src0_sel:DWORD src1_sel:BYTE_0
	v_and_b32_e32 v18, 32, v17
	v_bfe_i32 v17, v8, 0, 16
	v_add_lshl_u32 v8, v18, v17, 1
	s_waitcnt vmcnt(0)
	v_lshl_add_u32 v132, v13, 12, v8
	v_lshl_add_u32 v134, v12, 12, v8
	v_bfe_i32 v8, v14, 27, 1
	v_lshrrev_b32_e32 v8, 22, v8
	v_add_u32_e32 v8, v2, v8
	v_and_b32_e32 v8, 0xfffffc00, v8
	v_sub_u32_e32 v2, v2, v8
	v_lshrrev_b32_e32 v8, 4, v2
	v_ashrrev_i32_e32 v9, 31, v14
	v_bitop3_b32 v2, v8, v2, 32 bitop3:0x6c
	v_lshrrev_b32_e32 v9, 26, v9
	v_ashrrev_i32_e32 v8, 31, v2
	v_add_u32_e32 v9, v14, v9
	v_lshrrev_b32_e32 v8, 26, v8
	v_ashrrev_i32_e32 v19, 6, v9
	v_add_u32_e32 v8, v2, v8
	v_lshlrev_b32_e32 v9, 3, v19
	v_ashrrev_i32_e32 v18, 6, v8
	v_and_b32_e32 v9, -16, v9
	v_add_u32_e32 v9, v18, v9
	v_and_b32_e32 v12, 3, v18
	v_lshrrev_b32_e32 v13, 2, v9
	v_lshlrev_b32_e32 v20, 1, v9
	v_and_b32_e32 v8, 0xc0, v8
	v_and_or_b32 v12, v9, s4, v12
	v_and_b32_e32 v13, 4, v13
	v_and_b32_e32 v20, 24, v20
	v_sub_u32_e32 v2, v2, v8
	v_or3_b32 v12, v12, v13, v20
	v_lshlrev_b32_e32 v13, 5, v19
	v_ashrrev_i16_sdwa v2, v209, sext(v2) dst_sel:DWORD dst_unused:UNUSED_PAD src0_sel:DWORD src1_sel:BYTE_0
	s_ashr_i32 s8, s6, 6
	v_and_b32_e32 v13, 32, v13
	v_bfe_i32 v20, v2, 0, 16
	v_readlane_b32 s4, v251, 33
	s_lshl_b32 s27, s8, 10
	v_add_lshl_u32 v8, v13, v20, 1
	v_readlane_b32 s5, v251, 34
	v_readlane_b32 s10, v249, 19
	v_readlane_b32 s11, v249, 20
	v_lshl_add_u32 v2, v12, 12, v8
	v_lshl_add_u64 v[12:13], v[6:7], 0, s[4:5]
	s_add_i32 s29, s27, 0
	v_readlane_b32 s18, v249, 27
	v_readlane_b32 s19, v249, 28
	v_readfirstlane_b32 s24, v6
	v_readfirstlane_b32 s25, v7
	s_add_i32 m0, s29, 0x10000
	v_lshl_add_u64 v[6:7], v[12:13], 0, v[2:3]
	v_mov_b32_e32 v133, v3
	s_mov_b64 s[10:11], 0x80000
	v_lshl_add_u32 v136, v9, 12, v8
	v_readfirstlane_b32 s18, v12
	v_readfirstlane_b32 s19, v13
	global_load_lds_dwordx4 v[6:7], off
	v_lshl_add_u64 v[8:9], v[12:13], 0, v[132:133]
	s_add_i32 m0, s29, 0x12000
	v_lshl_add_u64 v[12:13], v[12:13], 0, s[10:11]
	v_readlane_b32 s4, v251, 37
	global_load_lds_dwordx4 v[8:9], off
	s_add_i32 m0, s29, 0x14000
	v_lshl_add_u64 v[22:23], v[12:13], 0, v[2:3]
	v_readlane_b32 s5, v251, 38
	global_load_lds_dwordx4 v[22:23], off
	v_lshl_add_u64 v[12:13], v[12:13], 0, v[132:133]
	s_add_i32 m0, s29, 0x16000
	v_lshl_add_u64 v[22:23], v[10:11], 0, s[4:5]
	v_mov_b32_e32 v137, v3
	v_readlane_b32 s16, v249, 25
	v_readlane_b32 s17, v249, 26
	v_readfirstlane_b32 s22, v10
	v_readfirstlane_b32 s23, v11
	global_load_lds_dwordx4 v[12:13], off
	v_lshl_add_u64 v[10:11], v[22:23], 0, v[136:137]
	s_mov_b32 m0, s29
	v_mov_b32_e32 v135, v3
	s_add_i32 s30, s29, 0x2000
	v_readfirstlane_b32 s16, v22
	v_readfirstlane_b32 s17, v23
	global_load_lds_dwordx4 v[10:11], off
	v_lshl_add_u64 v[12:13], v[22:23], 0, v[134:135]
	s_mov_b32 m0, s30
	v_lshl_add_u64 v[22:23], v[22:23], 0, s[10:11]
	s_add_i32 s33, s29, 0x4000
	global_load_lds_dwordx4 v[12:13], off
	v_lshl_add_u64 v[24:25], v[22:23], 0, v[136:137]
	s_mov_b32 m0, s33
	s_add_i32 s38, s29, 0x6000
	global_load_lds_dwordx4 v[24:25], off
	v_lshl_add_u64 v[22:23], v[22:23], 0, v[134:135]
	s_mov_b32 m0, s38
	s_ashr_i32 s7, s6, 8
	global_load_lds_dwordx4 v[22:23], off
	s_cmp_eq_u32 s7, 1
	s_cselect_b64 s[4:5], -1, 0
	s_cmp_lg_u32 s7, 1
	v_readlane_b32 s9, v249, 18
	v_readlane_b32 s12, v249, 21
	v_readlane_b32 s13, v249, 22
	v_readlane_b32 s14, v249, 23
	v_readlane_b32 s15, v249, 24
	v_readlane_b32 s20, v249, 29
	v_readlane_b32 s21, v249, 30
	s_cbranch_scc1 .LBB11_450
	s_barrier

; #define PG8_WAIT_V(n) asm volatile("s_waitcnt vmcnt(" #n ")" ::: "memory")
; #define PG8_BAR __builtin_amdgcn_s_barrier()
; template <class Epi, class Sched, bool ALIGN_EPI = false, bool SP2 = false>
; __device__ __forceinline__ void gemm_phase(PG8_LAS unsigned char* lds, const Gemm g, const Sched& S, const Epi& E) {
;     int tid_ = threadIdx.x; asm volatile("" : "+v"(tid_));
;     const int tid = tid_, wid = __builtin_amdgcn_readfirstlane(tid >> 6), lane = tid & 63, wr = wid >> 2, wc = wid & 3, fr = lane & 15, fq = lane >> 4;
;     const int K = g.K, nt = K / BK;
;     unsigned voffA[2], voffB[2];
; #pragma unroll
;     for (int i = 0; i < 2; ++i) { int R, C; stage_rc(tid * 16 + i * 8192, R, C); const int Rb = Epi::PERM ? ((R & ~31) + perm32(R & 31)) : R;
;         voffA[i] = (unsigned)(R * K + C) * 2u; voffB[i] = (unsigned)(Rb * K + C) * 2u; }
;     const size_t kstep = (size_t)(BK * 2);
;     const size_t hstep = (size_t)HALF * K * 2;
;     const size_t tstep = 2 * hstep;
;     const unsigned ldsw = (unsigned)wid * 1024u;
;     const int aoff = lds_byte(wr * 64 + fr, fq * 8), boff = lds_byte(wc * 32 + fr, fq * 8);
;     ...
;     Unit cur, nxt; int ui = 0;
;     if (!S.next(0, cur)) return;
;     f32x4 acc[2][2][4][2];
; #pragma unroll
;     for (int a = 0; a < 2; ++a)
; #pragma unroll
;         for (int b = 0; b < 2; ++b)
; #pragma unroll
;             for (int m = 0; m < 4; ++m)
; #pragma unroll
;                 for (int n = 0; n < 2; ++n) acc[a][b][m][n] = (f32x4){0.f, 0.f, 0.f, 0.f};
;     bf16x8 At[4][2], B0[2][2], B1[2][2];
;     const char* cA = (const char*)g.A + (size_t)cur.pm * tstep; const char* cB = (const char*)g.Bt + (size_t)cur.pn * tstep;
;     S.a_ready(cur);
;     if constexpr (SP2) {
;         PG8_STAGE(PG8_SB(0, 0), cB, voffB); PG8_STAGE(PG8_SB(0, 1), cB + hstep, voffB); PG8_STAGE(PG8_SA(0, 0), cA, voffA); PG8_STAGE(PG8_SA(0, 1), cA + hstep, voffA);
;         if (wr == 1) PG8_BAR;
;         PG8_WAIT_V(2); PG8_BAR;
;         PG8_STAGE(PG8_SB(1, 0), cB + kstep, voffB); PG8_STAGE(PG8_SA(1, 0), cA + kstep, voffA); PG8_STAGE(PG8_SB(1, 1), cB + hstep + kstep, voffB);
;         PG8_WAIT_V(6); PG8_BAR;
;     } else {
;         PG8_STAGE(PG8_SB(0, 0), cB, voffB); PG8_STAGE(PG8_SA(0, 0), cA, voffA); PG8_STAGE(PG8_SB(0, 1), cB + hstep, voffB); PG8_STAGE(PG8_SA(0, 1), cA + hstep, voffA);
;         if (wr == 1) PG8_BAR;
;         PG8_WAIT_V(4); PG8_BAR;
.LBB11_624:
	s_or_b64 exec, exec, s[2:3]
	s_waitcnt lgkmcnt(0)
	s_barrier
	s_cmp_lg_u32 s100, 1
	s_cbranch_scc1 .Lsg_xq
	v_readlane_b32 s101, v249, 0
	s_and_b32 s101, s101, 6
	s_lshl_b32 s101, s101, 8
	s_addk_i32 s101, 0x400
	v_readlane_b32 s100, v250, 49
	s_sub_u32 s100, s100, s101
	v_writelane_b32 v250, s100, 49
	s_nop 1
	v_readlane_b32 s100, v250, 50
	s_subb_u32 s100, s100, 0
	v_writelane_b32 v250, s100, 50
	s_nop 1
	v_readlane_b32 s100, v250, 51
	s_sub_u32 s100, s100, s101
	v_writelane_b32 v250, s100, 51
	s_nop 1
	v_readlane_b32 s100, v250, 52
	s_subb_u32 s100, s100, 0
	v_writelane_b32 v250, s100, 52
	s_nop 1
	v_readlane_b32 s100, v252, 11
	s_nop 3
	v_mov_b32_e32 v1, s100
	v_mov_b32_e32 v2, 8
	ds_write_b32 v1, v2
	s_waitcnt lgkmcnt(0)
	s_mov_b32 s100, 0
.Lsg_xq:
.LBB11_625:
	v_readlane_b32 s4, v250, 53
	v_and_b32_e32 v1, 63, v0
	s_mov_b64 s[2:3], 0
	v_readlane_b32 s1, v249, 40
	v_mov_b32_e32 v14, v0
	v_readlane_b32 s5, v250, 54
	s_andn2_b64 vcc, exec, s[4:5]
	v_readfirstlane_b32 s4, v14
	s_cbranch_vccnz .LBB11_645
	v_lshlrev_b32_e32 v2, 4, v14
	v_add_u32_e32 v8, 0x2000, v2
	v_ashrrev_i32_e32 v9, 31, v8
	v_lshrrev_b32_e32 v9, 22, v9
	v_add_u32_e32 v9, v8, v9
	v_ashrrev_i32_e32 v15, 10, v9
	v_mul_i32_i24_e32 v9, 0x400, v15
	v_sub_u32_e32 v8, v8, v9
	v_lshrrev_b32_e32 v9, 4, v8
	v_bitop3_b32 v8, v9, v8, 32 bitop3:0x6c
	v_ashrrev_i32_e32 v9, 31, v8
	v_readlane_b32 s8, v249, 17
	v_lshrrev_b32_e32 v9, 26, v9
	v_readlane_b32 s5, v252, 23
	v_mov_b64_e32 v[4:5], s[2:3]
	v_readlane_b32 s22, v249, 31
	v_readlane_b32 s23, v249, 32
	v_add_u32_e32 v9, v8, v9
	v_lshlrev_b32_e32 v12, 3, v15
	s_lshl_b32 s30, s5, 21
	v_lshl_add_u64 v[4:5], s[22:23], 0, v[4:5]
	s_mov_b64 s[2:3], 0x47a00000
	v_ashrrev_i32_e32 v16, 6, v9
	v_and_b32_e32 v12, -16, v12
	v_lshl_add_u64 v[10:11], v[4:5], 0, s[2:3]
	v_lshl_add_u64 v[6:7], v[4:5], 0, s[30:31]
	s_mov_b64 s[2:3], 0x28f00000
	v_add_u32_e32 v12, v16, v12
	v_lshl_add_u64 v[6:7], v[6:7], 0, s[2:3]
	v_and_b32_e32 v13, 3, v16
	s_mov_b32 s2, 0xfffe0
	v_lshrrev_b32_e32 v17, 2, v12
	v_lshlrev_b32_e32 v18, 1, v12
	v_and_b32_e32 v9, 0xc0, v9
	v_and_or_b32 v13, v12, s2, v13
	v_and_b32_e32 v17, 4, v17
	v_and_b32_e32 v18, 24, v18
	v_sub_u32_e32 v8, v8, v9
	v_or3_b32 v13, v13, v17, v18
	v_lshlrev_b32_e32 v17, 5, v15
	v_ashrrev_i16_sdwa v8, v209, sext(v8) dst_sel:DWORD dst_unused:UNUSED_PAD src0_sel:DWORD src1_sel:BYTE_0
	v_and_b32_e32 v18, 32, v17
	v_bfe_i32 v17, v8, 0, 16
	v_add_lshl_u32 v8, v18, v17, 1
	s_waitcnt vmcnt(0)
	v_lshl_add_u32 v132, v13, 12, v8
	v_lshl_add_u32 v134, v12, 12, v8
	v_bfe_i32 v8, v14, 27, 1
	v_lshrrev_b32_e32 v8, 22, v8
	v_add_u32_e32 v8, v2, v8
	v_and_b32_e32 v8, 0xfffffc00, v8
	v_sub_u32_e32 v2, v2, v8
	v_lshrrev_b32_e32 v8, 4, v2
	v_ashrrev_i32_e32 v9, 31, v14
	v_bitop3_b32 v2, v8, v2, 32 bitop3:0x6c
	v_lshrrev_b32_e32 v9, 26, v9
	v_ashrrev_i32_e32 v8, 31, v2
	v_add_u32_e32 v9, v14, v9
	v_lshrrev_b32_e32 v8, 26, v8
	v_ashrrev_i32_e32 v19, 6, v9
	v_add_u32_e32 v8, v2, v8
	v_lshlrev_b32_e32 v9, 3, v19
	v_ashrrev_i32_e32 v18, 6, v8
	v_and_b32_e32 v9, -16, v9
	v_add_u32_e32 v9, v18, v9
	v_and_b32_e32 v12, 3, v18
	v_lshrrev_b32_e32 v13, 2, v9
	v_lshlrev_b32_e32 v20, 1, v9
	v_and_b32_e32 v8, 0xc0, v8
	v_and_or_b32 v12, v9, s2, v12
	v_and_b32_e32 v13, 4, v13
	v_and_b32_e32 v20, 24, v20
	v_sub_u32_e32 v2, v2, v8
	v_or3_b32 v12, v12, v13, v20
	v_lshlrev_b32_e32 v13, 5, v19
	v_ashrrev_i16_sdwa v2, v209, sext(v2) dst_sel:DWORD dst_unused:UNUSED_PAD src0_sel:DWORD src1_sel:BYTE_0
	s_ashr_i32 s8, s4, 6
	v_and_b32_e32 v13, 32, v13
	v_bfe_i32 v20, v2, 0, 16
	v_readlane_b32 s2, v251, 49
	s_lshl_b32 s30, s8, 10
	v_add_lshl_u32 v8, v13, v20, 1
	v_readlane_b32 s3, v251, 50
	v_readlane_b32 s10, v249, 19
	v_readlane_b32 s11, v249, 20
	v_lshl_add_u32 v2, v12, 12, v8
	v_lshl_add_u64 v[12:13], v[6:7], 0, s[2:3]
	s_add_i32 s33, s30, 0
	v_readlane_b32 s20, v249, 29
	v_readlane_b32 s21, v249, 30
	v_readfirstlane_b32 s26, v6
	v_readfirstlane_b32 s27, v7
	s_add_i32 m0, s33, 0x10000
	v_lshl_add_u64 v[6:7], v[12:13], 0, v[2:3]
	v_mov_b32_e32 v133, v3
	s_mov_b64 s[10:11], 0x80000
	v_lshl_add_u32 v136, v9, 12, v8
	v_readfirstlane_b32 s20, v12
	v_readfirstlane_b32 s21, v13
	global_load_lds_dwordx4 v[6:7], off
	v_lshl_add_u64 v[8:9], v[12:13], 0, v[132:133]
	s_add_i32 m0, s33, 0x12000
	v_lshl_add_u64 v[12:13], v[12:13], 0, s[10:11]
	v_readlane_b32 s2, v252, 0
	global_load_lds_dwordx4 v[8:9], off
	s_add_i32 m0, s33, 0x14000
	v_lshl_add_u64 v[22:23], v[12:13], 0, v[2:3]
	v_readlane_b32 s3, v252, 1
	global_load_lds_dwordx4 v[22:23], off
	v_lshl_add_u64 v[12:13], v[12:13], 0, v[132:133]
	s_add_i32 m0, s33, 0x16000
	v_lshl_add_u64 v[22:23], v[10:11], 0, s[2:3]
	v_mov_b32_e32 v137, v3
	v_readlane_b32 s18, v249, 27
	v_readlane_b32 s19, v249, 28
	v_readfirstlane_b32 s24, v10
	v_readfirstlane_b32 s25, v11
	global_load_lds_dwordx4 v[12:13], off
	v_lshl_add_u64 v[10:11], v[22:23], 0, v[136:137]
	s_mov_b32 m0, s33
	v_mov_b32_e32 v135, v3
	s_add_i32 s36, s33, 0x2000
	v_readfirstlane_b32 s18, v22
	v_readfirstlane_b32 s19, v23
	global_load_lds_dwordx4 v[10:11], off
	v_lshl_add_u64 v[12:13], v[22:23], 0, v[134:135]
	s_mov_b32 m0, s36
	v_lshl_add_u64 v[22:23], v[22:23], 0, s[10:11]
	s_add_i32 s37, s33, 0x4000
	global_load_lds_dwordx4 v[12:13], off
	v_lshl_add_u64 v[24:25], v[22:23], 0, v[136:137]
	s_mov_b32 m0, s37
	s_add_i32 s38, s33, 0x6000
	global_load_lds_dwordx4 v[24:25], off
	v_lshl_add_u64 v[22:23], v[22:23], 0, v[134:135]
	s_mov_b32 m0, s38
	s_ashr_i32 s5, s4, 8
	global_load_lds_dwordx4 v[22:23], off
	s_cmp_eq_u32 s5, 1
	s_cselect_b64 s[2:3], -1, 0
	s_cmp_lg_u32 s5, 1
	v_readlane_b32 s9, v249, 18
	v_readlane_b32 s12, v249, 21
	v_readlane_b32 s13, v249, 22
	v_readlane_b32 s14, v249, 23
	v_readlane_b32 s15, v249, 24
	v_readlane_b32 s16, v249, 25
	v_readlane_b32 s17, v249, 26
	s_cbranch_scc1 .LBB11_628
	s_barrier

; #define LAS __attribute__((address_space(3)))
; __device__ __forceinline__ unsigned xb_ld(unsigned* p)              { return __hip_atomic_load(p, __ATOMIC_RELAXED, __HIP_MEMORY_SCOPE_AGENT); }
; __device__ __forceinline__ unsigned xb_add(unsigned* p, unsigned v) { return __hip_atomic_fetch_add(p, v, __ATOMIC_RELAXED, __HIP_MEMORY_SCOPE_AGENT); }
; DEVI int otid() { int t = threadIdx.x; asm volatile("" : "+v"(t)); return t; }
; __device__ __forceinline__ void xcd_barrier(const XcdBarrier& b) {
;     asm volatile("s_waitcnt vmcnt(0)" ::: "memory");
;     __syncthreads();
;     if (threadIdx.x == 0) {
;         unsigned* bar = b.bar;
;         __builtin_amdgcn_s_waitcnt(0);
;         unsigned nloc = b.st[0], nx = b.st[1];
;         if (nloc == 0u) { xcd_barrier_complete(bar, b.x, nloc, nx); b.st[0] = nloc; b.st[1] = nx; }
;         const unsigned old = xb_add(&bar[XB_XSUB(b.x)], 1u);
;         const unsigned gen = old / nloc;
;         if (old + 1u == (gen + 1u) * nloc) {
;             __builtin_amdgcn_fence(__ATOMIC_RELEASE, "agent");
;             asm volatile("s_waitcnt vmcnt(0)" ::: "memory");
;             const unsigned og = xb_add(&bar[XB_TOP], 1u);
;             const unsigned tg = og / nx;
;             if (og + 1u == (tg + 1u) * nx) xb_add(&bar[XB_TOPGEN], 1u);
;             else XB_SPIN(xb_ld(&bar[XB_TOPGEN]) == tg, bar);
;             __builtin_amdgcn_fence(__ATOMIC_ACQUIRE, "agent");
;             xb_add(&bar[XB_XGEN(b.x)], 1u);
;             asm volatile("s_waitcnt vmcnt(0)" ::: "memory");
;         } else {
;             XB_SPIN(xb_ld(&bar[XB_XGEN(b.x)]) == gen, bar);
;             __builtin_amdgcn_fence(__ATOMIC_ACQUIRE, "agent");
;             asm volatile("s_waitcnt vmcnt(0)" ::: "memory");
;         }
;     }
;     __syncthreads();
; DEVI void cross_phase(LAS unsigned char* lds, const bf16_t* XQ, const bf16_t* KVX, bf16_t* XO, int layer) {
;     const int wid = otid() >> 6;
;     for (int u = blockIdx.x; u < NB * 4 * 8; u += gridDim.x) {
;         const int qb = u & 7, h = (u >> 3) & 3, b = u >> 5; const int m0 = b * SEQ + qb * 256 + wid * 32;
;         attn_unit<M_CROSS>(lds, XQ + (size_t)m0 * 512 + h * HD, 512, KVX + (size_t)(b * MEML) * 4096 + layer * 1024 + h * HD, KVX + (size_t)(b * MEML) * 4096 + layer * 1024 + 512 + h * HD, 4096,
;                            XO + (size_t)m0 * 512 + h * HD, 512, 0, 4, 1, 0, 1 << 30, 0);
;     }
.LBB11_822:
	s_or_b64 exec, exec, s[2:3]
	s_waitcnt lgkmcnt(0)
	s_barrier
	s_cmp_lg_u32 s100, 0
	s_cbranch_scc1 .Lsp_xatt
	v_readlane_b32 s101, v249, 0
	s_and_b32 s101, s101, 6
	s_lshl_b32 s101, s101, 8
	s_addk_i32 s101, 0x400
	v_readlane_b32 s100, v250, 49
	s_add_u32 s100, s100, s101
	v_writelane_b32 v250, s100, 49
	s_nop 1
	v_readlane_b32 s100, v250, 50
	s_addc_u32 s100, s100, 0
	v_writelane_b32 v250, s100, 50
	s_nop 1
	v_readlane_b32 s100, v250, 51
	s_add_u32 s100, s100, s101
	v_writelane_b32 v250, s100, 51
	s_nop 1
	v_readlane_b32 s100, v250, 52
	s_addc_u32 s100, s100, 0
	v_writelane_b32 v250, s100, 52
	s_nop 1
	v_readlane_b32 s100, v252, 11
	s_nop 3
	v_mov_b32_e32 v1, s100
	v_mov_b32_e32 v2, 2
	ds_write_b32 v1, v2
	s_waitcnt lgkmcnt(0)
	s_mov_b32 s100, 1
.Lsp_xatt:
.LBB11_823:
	v_readlane_b32 s1, v249, 40
	s_mov_b64 s[2:3], 0
	v_and_b32_e32 v1, 63, v0
	v_readlane_b32 s4, v251, 12
	v_readlane_b32 s5, v251, 13
	v_mov_b32_e32 v1, v0
	s_andn2_b64 vcc, exec, s[4:5]
	s_cbranch_vccnz .LBB11_843
	v_readlane_b32 s8, v249, 17
	v_mov_b64_e32 v[4:5], s[2:3]
	v_readlane_b32 s22, v249, 31
	v_readlane_b32 s23, v249, 32
	s_mov_b64 s[2:3], 0x5b200000
	v_ashrrev_i32_e32 v1, 1, v1
	v_lshl_add_u64 v[6:7], s[22:23], 0, v[4:5]
	v_lshl_add_u64 v[148:149], v[6:7], 0, s[2:3]
	s_mov_b64 s[2:3], 0x5ba00000
	v_lshl_add_u64 v[150:151], v[6:7], 0, s[2:3]
	v_readlane_b32 s2, v252, 17
	v_readlane_b32 s3, v252, 18
	s_lshl_b64 s[2:3], s[2:3], 9
	s_and_b32 s1, s2, 0xfffff800
	v_readlane_b32 s2, v252, 23
	s_lshl_b32 s30, s2, 11
	s_add_u32 s2, s22, s1
	v_lshl_add_u64 v[6:7], v[6:7], 0, s[30:31]
	s_mov_b64 s[4:5], 0x5c200000
	s_addc_u32 s3, s23, s3
	v_and_b32_e32 v1, 0xffffffe0, v1
	v_lshl_add_u64 v[152:153], v[6:7], 0, s[4:5]
	v_lshl_add_u64 v[154:155], s[2:3], 0, v[4:5]
	v_readlane_b32 s1, v251, 57
	v_readlane_b32 s8, v255, 9
	v_readlane_b32 s9, v249, 18
	v_readlane_b32 s10, v249, 19
	v_readlane_b32 s11, v249, 20
	v_readlane_b32 s12, v249, 21
	v_readlane_b32 s13, v249, 22
	v_readlane_b32 s14, v249, 23
	v_readlane_b32 s15, v249, 24
	v_readlane_b32 s16, v249, 25
	v_readlane_b32 s17, v249, 26
	v_readlane_b32 s18, v249, 27
	v_readlane_b32 s19, v249, 28
	v_readlane_b32 s20, v249, 29
	v_readlane_b32 s21, v249, 30
	s_branch .LBB11_826

; #define LAS __attribute__((address_space(3)))
; DEVI int otid() { int t = threadIdx.x; asm volatile("" : "+v"(t)); return t; }
; DEVI void stick_phase(LAS unsigned char* lds, const bf16_t* QKV, bf16_t* O) {
;     const int wid = otid() >> 6;
;     for (int u = blockIdx.x; u < NB * 16 * 4; u += gridDim.x) {
;         const int pq = u & 3, h = (u >> 2) & 15, b = u >> 6;
; #pragma unroll 1
;         for (int s = 0; s < 2; ++s) { const int qb = s == 0 ? 7 - pq : pq; const int tw = qb * 256 + wid * 32, m0 = b * SEQ + tw, cw = tw >> 6;
;             attn_unit<M_STICK>(lds, QKV + (size_t)m0 * ODD_COLS + h * HD, ODD_COLS, QKV + (size_t)(b * SEQ) * ODD_COLS + 2048 + h * HD, QKV + (size_t)(b * SEQ) * ODD_COLS + 4096 + h * HD, ODD_COLS,
;                                O + (size_t)m0 * DM + h * HD, DM, 4 * qb + 3, 4 * qb + 4, -1, 0, cw, tw); }
.LBB11_976:
	v_readlane_b32 s1, v249, 40
	s_mov_b64 s[2:3], 0
	v_and_b32_e32 v1, 63, v0
	v_readlane_b32 s4, v251, 16
	v_readlane_b32 s5, v251, 17
	v_mov_b32_e32 v1, v0
	s_andn2_b64 vcc, exec, s[4:5]
	s_cbranch_vccnz .LBB11_1004
	v_readlane_b32 s4, v249, 17
	v_mov_b64_e32 v[4:5], s[2:3]
	v_readlane_b32 s18, v249, 31
	v_readlane_b32 s19, v249, 32
	s_mov_b64 s[2:3], 0x53200000
	v_ashrrev_i32_e32 v1, 1, v1
	v_lshl_add_u64 v[116:117], s[18:19], 0, v[4:5]
	v_lshl_add_u64 v[118:119], v[116:117], 0, s[2:3]
	s_mov_b64 s[2:3], 0x59200000
	v_readlane_b32 s1, v255, 8
	v_lshl_add_u64 v[120:121], v[116:117], 0, s[2:3]
	s_waitcnt vmcnt(0)
	v_and_b32_e32 v137, 0xffffffe0, v1
	v_readlane_b32 s2, v251, 59
	s_mov_b32 s4, s1
	v_readlane_b32 s5, v249, 18
	v_readlane_b32 s6, v249, 19
	v_readlane_b32 s7, v249, 20
	v_readlane_b32 s8, v249, 21
	v_readlane_b32 s9, v249, 22
	v_readlane_b32 s10, v249, 23
	v_readlane_b32 s11, v249, 24
	v_readlane_b32 s12, v249, 25
	v_readlane_b32 s13, v249, 26
	v_readlane_b32 s14, v249, 27
	v_readlane_b32 s15, v249, 28
	v_readlane_b32 s16, v249, 29
	v_readlane_b32 s17, v249, 30
	s_branch .LBB11_979

; #define PG8_WAIT_V(n) asm volatile("s_waitcnt vmcnt(" #n ")" ::: "memory")
; #define PG8_BAR __builtin_amdgcn_s_barrier()
; template <class Epi, class Sched, bool ALIGN_EPI = false, bool SP2 = false>
; __device__ __forceinline__ void gemm_phase(PG8_LAS unsigned char* lds, const Gemm g, const Sched& S, const Epi& E) {
;     int tid_ = threadIdx.x; asm volatile("" : "+v"(tid_));
;     const int tid = tid_, wid = __builtin_amdgcn_readfirstlane(tid >> 6), lane = tid & 63, wr = wid >> 2, wc = wid & 3, fr = lane & 15, fq = lane >> 4;
;     const int K = g.K, nt = K / BK;
;     unsigned voffA[2], voffB[2];
; #pragma unroll
;     for (int i = 0; i < 2; ++i) { int R, C; stage_rc(tid * 16 + i * 8192, R, C); const int Rb = Epi::PERM ? ((R & ~31) + perm32(R & 31)) : R;
;         voffA[i] = (unsigned)(R * K + C) * 2u; voffB[i] = (unsigned)(Rb * K + C) * 2u; }
;     const size_t kstep = (size_t)(BK * 2);
;     const size_t hstep = (size_t)HALF * K * 2;
;     const size_t tstep = 2 * hstep;
;     const unsigned ldsw = (unsigned)wid * 1024u;
;     const int aoff = lds_byte(wr * 64 + fr, fq * 8), boff = lds_byte(wc * 32 + fr, fq * 8);
;     ...
;     Unit cur, nxt; int ui = 0;
;     if (!S.next(0, cur)) return;
;     f32x4 acc[2][2][4][2];
; #pragma unroll
;     for (int a = 0; a < 2; ++a)
; #pragma unroll
;         for (int b = 0; b < 2; ++b)
; #pragma unroll
;             for (int m = 0; m < 4; ++m)
; #pragma unroll
;                 for (int n = 0; n < 2; ++n) acc[a][b][m][n] = (f32x4){0.f, 0.f, 0.f, 0.f};
;     bf16x8 At[4][2], B0[2][2], B1[2][2];
;     const char* cA = (const char*)g.A + (size_t)cur.pm * tstep; const char* cB = (const char*)g.Bt + (size_t)cur.pn * tstep;
;     S.a_ready(cur);
;     if constexpr (SP2) {
;         PG8_STAGE(PG8_SB(0, 0), cB, voffB); PG8_STAGE(PG8_SB(0, 1), cB + hstep, voffB); PG8_STAGE(PG8_SA(0, 0), cA, voffA); PG8_STAGE(PG8_SA(0, 1), cA + hstep, voffA);
;         if (wr == 1) PG8_BAR;
;         PG8_WAIT_V(2); PG8_BAR;
;         PG8_STAGE(PG8_SB(1, 0), cB + kstep, voffB); PG8_STAGE(PG8_SA(1, 0), cA + kstep, voffA); PG8_STAGE(PG8_SB(1, 1), cB + hstep + kstep, voffB);
;         PG8_WAIT_V(6); PG8_BAR;
;     } else {
;         PG8_STAGE(PG8_SB(0, 0), cB, voffB); PG8_STAGE(PG8_SA(0, 0), cA, voffA); PG8_STAGE(PG8_SB(0, 1), cB + hstep, voffB); PG8_STAGE(PG8_SA(0, 1), cA + hstep, voffA);
;         if (wr == 1) PG8_BAR;
;         PG8_WAIT_V(4); PG8_BAR;
.Lsg_ev:
.LBB11_1062:
	v_readlane_b32 s4, v251, 18
	v_readlane_b32 s1, v249, 40
	s_mov_b64 s[2:3], 0
	v_and_b32_e32 v1, 63, v0
	v_mov_b32_e32 v2, v0
	v_readlane_b32 s5, v251, 19
	s_andn2_b64 vcc, exec, s[4:5]
	v_readfirstlane_b32 s4, v2
	s_cbranch_vccnz .LBB11_1089
	v_lshlrev_b32_e32 v6, 4, v2
	v_add_u32_e32 v7, 0x2000, v6
	v_ashrrev_i32_e32 v10, 31, v7
	v_lshrrev_b32_e32 v10, 22, v10
	v_add_u32_e32 v10, v7, v10
	v_ashrrev_i32_e32 v12, 10, v10
	v_mul_i32_i24_e32 v10, 0x400, v12
	v_sub_u32_e32 v7, v7, v10
	v_lshrrev_b32_e32 v10, 4, v7
	v_bitop3_b32 v7, v10, v7, 32 bitop3:0x6c
	v_ashrrev_i32_e32 v10, 31, v7
	s_mul_i32 s30, s18, 0x1600000
	v_readlane_b32 s8, v249, 17
	v_lshrrev_b32_e32 v10, 26, v10
	v_mov_b64_e32 v[4:5], s[2:3]
	v_readlane_b32 s22, v249, 31
	v_readlane_b32 s23, v249, 32
	v_add_u32_e32 v10, v7, v10
	v_lshlrev_b32_e32 v11, 3, v12
	v_lshl_add_u64 v[148:149], s[22:23], 0, v[4:5]
	s_mov_b64 s[2:3], 0x47a00000
	v_ashrrev_i32_e32 v13, 6, v10
	v_and_b32_e32 v11, -16, v11
	v_lshl_add_u64 v[8:9], v[148:149], 0, s[2:3]
	v_lshl_add_u64 v[4:5], v[148:149], 0, s[30:31]
	s_mov_b64 s[2:3], 0x21300000
	v_add_u32_e32 v11, v13, v11
	v_lshl_add_u64 v[4:5], v[4:5], 0, s[2:3]
	v_and_b32_e32 v14, 3, v13
	s_mov_b32 s2, 0xfffe0
	v_lshrrev_b32_e32 v15, 2, v11
	v_lshlrev_b32_e32 v16, 1, v11
	v_and_b32_e32 v10, 0xc0, v10
	v_and_or_b32 v14, v11, s2, v14
	v_and_b32_e32 v15, 4, v15
	v_and_b32_e32 v16, 24, v16
	v_sub_u32_e32 v7, v7, v10
	v_or3_b32 v15, v14, v15, v16
	v_lshlrev_b32_e32 v14, 5, v12
	v_ashrrev_i16_sdwa v7, v209, sext(v7) dst_sel:DWORD dst_unused:UNUSED_PAD src0_sel:DWORD src1_sel:BYTE_0
	v_and_b32_e32 v16, 32, v14
	v_bfe_i32 v14, v7, 0, 16
	v_add_lshl_u32 v7, v16, v14, 1
	v_lshl_add_u32 v150, v15, 12, v7
	v_lshl_add_u32 v152, v11, 12, v7
	v_bfe_i32 v7, v2, 27, 1
	v_lshrrev_b32_e32 v7, 22, v7
	v_add_u32_e32 v7, v6, v7
	v_and_b32_e32 v7, 0xfffffc00, v7
	v_sub_u32_e32 v6, v6, v7
	v_lshrrev_b32_e32 v7, 4, v6
	v_ashrrev_i32_e32 v10, 31, v2
	v_bitop3_b32 v6, v7, v6, 32 bitop3:0x6c
	v_lshrrev_b32_e32 v10, 26, v10
	v_ashrrev_i32_e32 v7, 31, v6
	v_add_u32_e32 v10, v2, v10
	v_lshrrev_b32_e32 v7, 26, v7
	v_ashrrev_i32_e32 v16, 6, v10
	v_add_u32_e32 v7, v6, v7
	v_lshlrev_b32_e32 v10, 3, v16
	v_ashrrev_i32_e32 v15, 6, v7
	v_and_b32_e32 v10, -16, v10
	v_add_u32_e32 v10, v15, v10
	v_and_b32_e32 v11, 3, v15
	v_lshrrev_b32_e32 v17, 2, v10
	v_lshlrev_b32_e32 v18, 1, v10
	v_and_b32_e32 v7, 0xc0, v7
	v_and_or_b32 v11, v10, s2, v11
	v_and_b32_e32 v17, 4, v17
	v_and_b32_e32 v18, 24, v18
	v_sub_u32_e32 v6, v6, v7
	v_or3_b32 v11, v11, v17, v18
	v_lshlrev_b32_e32 v17, 5, v16
	v_ashrrev_i16_sdwa v6, v209, sext(v6) dst_sel:DWORD dst_unused:UNUSED_PAD src0_sel:DWORD src1_sel:BYTE_0
	s_ashr_i32 s6, s4, 6
	v_and_b32_e32 v18, 32, v17
	v_bfe_i32 v17, v6, 0, 16
	v_readlane_b32 s2, v251, 21
	s_lshl_b32 s24, s6, 10
	v_add_lshl_u32 v6, v18, v17, 1
	v_readlane_b32 s3, v251, 22
	v_readlane_b32 s9, v249, 18
	v_lshl_add_u32 v154, v11, 12, v6
	v_lshl_add_u32 v156, v10, 12, v6
	v_lshl_add_u64 v[10:11], v[4:5], 0, s[2:3]
	s_add_i32 s25, s24, 0
	v_mov_b32_e32 v155, v3
	v_readlane_b32 s16, v249, 25
	v_readlane_b32 s17, v249, 26
	v_readfirstlane_b32 s22, v4
	v_readfirstlane_b32 s23, v5
	s_add_i32 m0, s25, 0x10000
	v_lshl_add_u64 v[4:5], v[10:11], 0, v[154:155]
	v_mov_b32_e32 v151, v3
	s_mov_b64 s[8:9], 0x80000
	v_readfirstlane_b32 s16, v10
	v_readfirstlane_b32 s17, v11
	global_load_lds_dwordx4 v[4:5], off
	v_lshl_add_u64 v[6:7], v[10:11], 0, v[150:151]
	s_add_i32 m0, s25, 0x12000
	v_lshl_add_u64 v[10:11], v[10:11], 0, s[8:9]
	v_readlane_b32 s2, v251, 25
	global_load_lds_dwordx4 v[6:7], off
	s_add_i32 m0, s25, 0x14000
	v_lshl_add_u64 v[18:19], v[10:11], 0, v[154:155]
	v_readlane_b32 s3, v251, 26
	v_readlane_b32 s20, v249, 29
	v_readlane_b32 s21, v249, 30
	global_load_lds_dwordx4 v[18:19], off
	v_lshl_add_u64 v[10:11], v[10:11], 0, v[150:151]
	s_add_i32 m0, s25, 0x16000
	v_lshl_add_u64 v[18:19], v[8:9], 0, s[2:3]
	v_mov_b32_e32 v157, v3
	v_readlane_b32 s14, v249, 23
	v_readlane_b32 s15, v249, 24
	v_readfirstlane_b32 s20, v8
	v_readfirstlane_b32 s21, v9
	global_load_lds_dwordx4 v[10:11], off
	v_lshl_add_u64 v[8:9], v[18:19], 0, v[156:157]
	s_mov_b32 m0, s25
	v_mov_b32_e32 v153, v3
	s_add_i32 s26, s25, 0x2000
	v_readfirstlane_b32 s14, v18
	v_readfirstlane_b32 s15, v19
	global_load_lds_dwordx4 v[8:9], off
	v_lshl_add_u64 v[10:11], v[18:19], 0, v[152:153]
	s_mov_b32 m0, s26
	v_lshl_add_u64 v[18:19], v[18:19], 0, s[8:9]
	s_add_i32 s27, s25, 0x4000
	global_load_lds_dwordx4 v[10:11], off
	v_lshl_add_u64 v[20:21], v[18:19], 0, v[156:157]
	s_mov_b32 m0, s27
	s_add_i32 s28, s25, 0x6000
	global_load_lds_dwordx4 v[20:21], off
	v_lshl_add_u64 v[18:19], v[18:19], 0, v[152:153]
	s_mov_b32 m0, s28
	s_ashr_i32 s5, s4, 8
	global_load_lds_dwordx4 v[18:19], off
	s_cmp_eq_u32 s5, 1
	s_cselect_b64 s[2:3], -1, 0
	s_cmp_lg_u32 s5, 1
	v_readlane_b32 s10, v249, 19
	v_readlane_b32 s11, v249, 20
	v_readlane_b32 s12, v249, 21
	v_readlane_b32 s13, v249, 22
	v_readlane_b32 s18, v249, 27
	v_readlane_b32 s19, v249, 28
	s_cbranch_scc1 .LBB11_1065
	s_barrier

; __device__ __forceinline__ void xcd_barrier(const XcdBarrier& b) {
;     asm volatile("s_waitcnt vmcnt(0)" ::: "memory");
;     __syncthreads();
;     if (threadIdx.x == 0) {
;         unsigned* bar = b.bar;
;         __builtin_amdgcn_s_waitcnt(0);
;         unsigned nloc = b.st[0], nx = b.st[1];
;         if (nloc == 0u) { xcd_barrier_complete(bar, b.x, nloc, nx); b.st[0] = nloc; b.st[1] = nx; }
;         const unsigned old = xb_add(&bar[XB_XSUB(b.x)], 1u);
;         const unsigned gen = old / nloc;
;         if (old + 1u == (gen + 1u) * nloc) {
;             __builtin_amdgcn_fence(__ATOMIC_RELEASE, "agent");
;             asm volatile("s_waitcnt vmcnt(0)" ::: "memory");
;             const unsigned og = xb_add(&bar[XB_TOP], 1u);
;             const unsigned tg = og / nx;
;             if (og + 1u == (tg + 1u) * nx) xb_add(&bar[XB_TOPGEN], 1u);
;             else XB_SPIN(xb_ld(&bar[XB_TOPGEN]) == tg, bar);
;             __builtin_amdgcn_fence(__ATOMIC_ACQUIRE, "agent");
;             xb_add(&bar[XB_XGEN(b.x)], 1u);
;             asm volatile("s_waitcnt vmcnt(0)" ::: "memory");
;         } else {
;             XB_SPIN(xb_ld(&bar[XB_XGEN(b.x)]) == gen, bar);
;             __builtin_amdgcn_fence(__ATOMIC_ACQUIRE, "agent");
; DEVI void indexer_phase(LAS unsigned char* lds, const bf16_t* EV, float* SC) {
;     const int tid = otid(), wid = tid >> 6, lane = tid & 63, r32 = lane & 31, hi = lane >> 5;
;     LAS float* wl = (LAS float*)(lds + 66560);
;     for (int u = blockIdx.x; u < NB * 64; u += gridDim.x) {
;         const int g = u & 63, b = u >> 6, m0 = b * SEQ + 32 * g, nt = (g >> 1) + 1;
;         { bf16x8 qv[8];
; #pragma unroll
;           for (int k = 0; k < 8; ++k) { const int idx = tid + 512 * k, row = idx >> 7, ch = idx & 127; qv[k] = *(const bf16x8*)(EV + (size_t)(m0 + row) * EVP + EV_QI + ch * 8); }
;           asm volatile("" : "+v"(qv[0]), "+v"(qv[1]), "+v"(qv[2]), "+v"(qv[3]), "+v"(qv[4]), "+v"(qv[5]), "+v"(qv[6]), "+v"(qv[7]));
; #pragma unroll
;           for (int k = 0; k < 8; ++k) { const int idx = tid + 512 * k, row = idx >> 7, ch = idx & 127; *(LAS bf16x8*)(lds + row * 2064 + ch * 16) = qv[k]; } }
;         wl[tid] = bf2f(EV[(size_t)(m0 + (tid & 31)) * EVP + EV_WI + (tid >> 5)]);
;         asm volatile("s_waitcnt lgkmcnt(0)" ::: "memory"); __builtin_amdgcn_s_barrier(); asm volatile("" ::: "memory");
.LBB11_1266:
	s_or_b64 exec, exec, s[2:3]
	v_readlane_b32 s4, v249, 17
	v_readlane_b32 s18, v249, 31
	v_readlane_b32 s19, v249, 32
	s_waitcnt lgkmcnt(0)
	s_barrier
	v_readlane_b32 s5, v249, 18
	v_readlane_b32 s6, v249, 19
	v_readlane_b32 s7, v249, 20
	v_readlane_b32 s8, v249, 21
	v_readlane_b32 s9, v249, 22
	v_readlane_b32 s10, v249, 23
	v_readlane_b32 s11, v249, 24
	v_readlane_b32 s12, v249, 25
	v_readlane_b32 s13, v249, 26
	v_readlane_b32 s14, v249, 27
	v_readlane_b32 s15, v249, 28
	v_readlane_b32 s16, v249, 29
	v_readlane_b32 s17, v249, 30
	s_cmp_lg_u32 s100, 0
	s_cbranch_scc1 .Lsp_idx
	v_readlane_b32 s101, v249, 0
	s_and_b32 s101, s101, 6
	s_lshl_b32 s101, s101, 8
	s_addk_i32 s101, 0x400
	v_readlane_b32 s100, v250, 49
	s_add_u32 s100, s100, s101
	v_writelane_b32 v250, s100, 49
	s_nop 1
	v_readlane_b32 s100, v250, 50
	s_addc_u32 s100, s100, 0
	v_writelane_b32 v250, s100, 50
	s_nop 1
	v_readlane_b32 s100, v250, 51
	s_add_u32 s100, s100, s101
	v_writelane_b32 v250, s100, 51
	s_nop 1
	v_readlane_b32 s100, v250, 52
	s_addc_u32 s100, s100, 0
	v_writelane_b32 v250, s100, 52
	s_nop 1
	v_readlane_b32 s100, v252, 11
	s_nop 3
	v_mov_b32_e32 v1, s100
	v_mov_b32_e32 v2, 2
	ds_write_b32 v1, v2
	s_waitcnt lgkmcnt(0)
	s_mov_b32 s100, 1
.Lsp_idx:
.LBB11_1267:
	v_readlane_b32 s1, v249, 40
	s_mov_b64 s[2:3], 0
	v_and_b32_e32 v1, 63, v0
	s_add_u32 s2, s18, s2
	v_readlane_b32 s4, v251, 16
	s_addc_u32 s3, s19, s3
	v_readlane_b32 s5, v251, 17
	s_add_u32 s8, s2, 0x53200000
	s_addc_u32 s9, s3, 0
	v_cndmask_b32_e64 v1, 0, 1, s[4:5]
	v_mov_b32_e32 v4, v0
	v_cmp_ne_u32_e64 s[36:37], 1, v1
	s_andn2_b64 vcc, exec, s[4:5]
	s_cbranch_vccnz .LBB11_1275
	s_waitcnt vmcnt(0)
	v_and_b32_e32 v140, 31, v4
	v_bfe_u32 v2, v4, 5, 1
	v_lshlrev_b32_e32 v8, 3, v2
	v_lshl_add_u32 v142, v2, 4, 0
	v_lshlrev_b32_e32 v144, 2, v2
	v_lshlrev_b32_e32 v2, 2, v140
	v_lshl_add_u64 v[10:11], s[2:3], 0, v[2:3]
	v_add_u32_e32 v2, 0x200, v4
	v_ashrrev_i32_e32 v146, 7, v2
	v_add_u32_e32 v2, 0x400, v4
	v_ashrrev_i32_e32 v147, 7, v2
	v_add_u32_e32 v2, 0x600, v4
	v_ashrrev_i32_e32 v148, 7, v2
	v_add_u32_e32 v2, 0x800, v4
	v_ashrrev_i32_e32 v149, 7, v2
	v_add_u32_e32 v2, 0xa00, v4
	v_ashrrev_i32_e32 v150, 7, v2
	v_add_u32_e32 v2, 0xc00, v4
	v_lshlrev_b32_e32 v5, 4, v4
	v_readlane_b32 s1, v252, 13
	v_ashrrev_i32_e32 v151, 7, v2
	v_add_u32_e32 v2, 0xe00, v4
	v_and_b32_e32 v6, 0x7f0, v5
	v_lshl_add_u32 v141, v4, 2, s1
	s_movk_i32 s1, 0x810
	s_mov_b64 s[4:5], 0x5ce00000
	v_ashrrev_i32_e32 v145, 7, v4
	v_ashrrev_i32_e32 v152, 7, v2
	v_ashrrev_i32_e32 v1, 6, v4
	v_add_u32_e32 v5, 0, v6
	v_ashrrev_i32_e32 v68, 5, v4
	v_lshl_add_u64 v[70:71], v[10:11], 0, s[4:5]
	v_mul_lo_u32 v2, v145, s1
	v_mul_lo_u32 v4, v146, s1
	v_mul_lo_u32 v9, v147, s1
	v_mul_lo_u32 v10, v148, s1
	v_mul_lo_u32 v11, v149, s1
	v_mul_lo_u32 v12, v150, s1
	v_mul_lo_u32 v13, v151, s1
	v_mul_lo_u32 v14, v152, s1
	v_mov_b32_e32 v7, v3
	v_ashrrev_i32_e32 v69, 31, v68
	v_mad_u32_u24 v143, v140, s1, v142
	v_lshl_add_u64 v[72:73], s[8:9], 0, v[6:7]
	v_add_u32_e32 v153, v5, v2
	v_add_u32_e32 v154, v5, v4
	v_add_u32_e32 v155, v5, v9
	v_add_u32_e32 v156, v5, v10
	v_add_u32_e32 v157, v5, v11
	v_add_u32_e32 v158, v5, v12
	v_add_u32_e32 v159, v5, v13
	v_add_u32_e32 v160, v5, v14
	v_lshlrev_b32_e32 v2, 1, v8
	v_readlane_b32 s1, v255, 8
	s_branch .LBB11_1270

; #define LAS __attribute__((address_space(3)))
; DEVI int otid() { int t = threadIdx.x; asm volatile("" : "+v"(t)); return t; }
; DEVI void band_phase(LAS unsigned char* lds, const bf16_t* EV, bf16_t* O, const float* relb  ) {
;     const int wid = otid() >> 6;
;     for (int u = blockIdx.x; u < NB * 8 * 8; u += gridDim.x) {
;         const int qb = 7 - ((u >> 3) & 7), h = u & 7, b = u >> 6;
;         const int tw = qb * 256 + wid * 32, m0 = b * SEQ + tw, cw = tw >> 6;
;         { const int tb = otid(); if (tb < RELSZ) ((LAS float*)(lds + OFF_BIAS))[tb] = relb[h * RELSZ + tb] * 1.4426950408889634f; }
;         const int jlo = (4 * qb - 8) < 0 ? 0 : 4 * qb - 8, jhi = 4 * qb + 3;
;         attn_unit<M_BAND>(lds, EV + (size_t)m0 * EVP + EV_QB + h * HD, EVP, EV + (size_t)(b * SEQ) * EVP + EV_KB + h * HD, EV + (size_t)(b * SEQ) * EVP + EV_VB + h * HD, EVP,
;                           O + (size_t)m0 * DM + 1024 + h * HD, DM, jlo, jhi - jlo + 1, 1, cw - 8, cw, tw);
.LBB11_1275:
	v_mov_b32_e32 v1, v0
	s_and_b64 vcc, exec, s[36:37]
	s_cbranch_vccnz .LBB11_1301
	v_readlane_b32 s1, v252, 16
	s_and_b32 s1, s1, 8
	v_readlane_b32 s12, v249, 17
	s_mulk_i32 s1, 0x300
	v_readlane_b32 s18, v249, 23
	v_ashrrev_i32_e32 v1, 1, v1
	v_readlane_b32 s19, v249, 24
	s_add_u32 s10, s18, s1
	v_and_b32_e32 v1, 0xffffffe0, v1
	s_addc_u32 s11, s19, 0
	v_add_u32_e32 v183, 36, v1
	v_readlane_b32 s1, v255, 8
	v_readlane_b32 s13, v249, 18
	v_readlane_b32 s14, v249, 19
	v_readlane_b32 s15, v249, 20
	v_readlane_b32 s16, v249, 21
	v_readlane_b32 s17, v249, 22
	v_readlane_b32 s20, v249, 25
	v_readlane_b32 s21, v249, 26
	v_readlane_b32 s22, v249, 27
	v_readlane_b32 s23, v249, 28
	v_readlane_b32 s24, v249, 29
	v_readlane_b32 s25, v249, 30
	v_readlane_b32 s26, v249, 31
	v_readlane_b32 s27, v249, 32
	s_branch .LBB11_1278

; __device__ __forceinline__ unsigned xb_ld(unsigned* p)              { return __hip_atomic_load(p, __ATOMIC_RELAXED, __HIP_MEMORY_SCOPE_AGENT); }
; __device__ __forceinline__ unsigned xb_add(unsigned* p, unsigned v) { return __hip_atomic_fetch_add(p, v, __ATOMIC_RELAXED, __HIP_MEMORY_SCOPE_AGENT); }
; #define XB_SPIN(cond, bar) do { unsigned _sp = 0; while (cond) { __builtin_amdgcn_s_sleep(1); \
;     if ((++_sp & 255u) == 0u) { if (xb_ld(&(bar)[XB_TMO])) break; if (_sp > XB_SPIN_CAP) { atomicAdd(&(bar)[XB_TMO], 1u); break; } } } } while (0)
; __device__ __forceinline__ void xcd_barrier(const XcdBarrier& b) {
;     asm volatile("s_waitcnt vmcnt(0)" ::: "memory");
;     __syncthreads();
;     if (threadIdx.x == 0) {
;         unsigned* bar = b.bar;
;         __builtin_amdgcn_s_waitcnt(0);
;         unsigned nloc = b.st[0], nx = b.st[1];
;         if (nloc == 0u) { xcd_barrier_complete(bar, b.x, nloc, nx); b.st[0] = nloc; b.st[1] = nx; }
;         const unsigned old = xb_add(&bar[XB_XSUB(b.x)], 1u);
;         const unsigned gen = old / nloc;
;         if (old + 1u == (gen + 1u) * nloc) {
;             __builtin_amdgcn_fence(__ATOMIC_RELEASE, "agent");
;             asm volatile("s_waitcnt vmcnt(0)" ::: "memory");
;             const unsigned og = xb_add(&bar[XB_TOP], 1u);
;             const unsigned tg = og / nx;
;             if (og + 1u == (tg + 1u) * nx) xb_add(&bar[XB_TOPGEN], 1u);
;             else XB_SPIN(xb_ld(&bar[XB_TOPGEN]) == tg, bar);
;             __builtin_amdgcn_fence(__ATOMIC_ACQUIRE, "agent");
;             xb_add(&bar[XB_XGEN(b.x)], 1u);
;             asm volatile("s_waitcnt vmcnt(0)" ::: "memory");
;         } else {
;             XB_SPIN(xb_ld(&bar[XB_XGEN(b.x)]) == gen, bar);
;             __builtin_amdgcn_fence(__ATOMIC_ACQUIRE, "agent");
;             asm volatile("s_waitcnt vmcnt(0)" ::: "memory");
;         }
;     }
;     __syncthreads();
; __global__ void __launch_bounds__(512, 2) k_mega(MegaArgs a) {
;     ...
;                 STEP_BEGIN(base + 3, F_DSA) { fa::dsa_phase(lds, QKV, SC, O); } STEP_END
.LBB11_1302:
	v_readlane_b32 s1, v252, 24
	s_or_b32 s1, s1, 5
	v_readlane_b32 s4, v249, 35
	v_readlane_b32 s5, v249, 36
	s_cmp_le_i32 s4, s1
	s_cselect_b64 s[2:3], -1, 0
	s_cmp_lt_i32 s1, s5
	s_cselect_b64 s[4:5], -1, 0
	s_and_b64 s[2:3], s[2:3], s[4:5]
	s_andn2_b64 vcc, exec, s[2:3]
	s_cbranch_vccnz .LBB11_1315
	v_readlane_b32 s2, v249, 41
	v_readlane_b32 s3, v249, 42
	s_andn2_b64 vcc, exec, s[2:3]
	s_cbranch_vccnz .LBB11_1358
	s_waitcnt vmcnt(0)
	s_waitcnt vmcnt(0) lgkmcnt(0)
	s_barrier
	s_branch .LBB11_1358
	s_mov_b64 s[2:3], exec
	v_readlane_b32 s4, v249, 38
	v_readlane_b32 s5, v249, 39
	s_and_b64 s[4:5], s[2:3], s[4:5]
	s_mov_b64 exec, s[4:5]
	s_cbranch_execz .LBB11_1357
	v_readlane_b32 s1, v252, 10
	s_waitcnt vmcnt(0) expcnt(0) lgkmcnt(0)
	s_nop 0
	v_mov_b32_e32 v1, s1
	ds_read_b32 v4, v1
	v_readlane_b32 s1, v252, 11
	s_waitcnt lgkmcnt(0)
	v_cmp_ne_u32_e32 vcc, 0, v4
	v_mov_b32_e32 v1, s1
	ds_read_b32 v2, v1
	s_cbranch_vccnz .LBB11_1321
	v_readlane_b32 s6, v249, 33
	v_readlane_b32 s7, v249, 34
	s_load_dwordx2 s[4:5], s[6:7], 0x4
	v_readlane_b32 s1, v249, 37
	s_mov_b32 s10, 1
	s_waitcnt lgkmcnt(0)
	s_mul_i32 s1, s4, s1
	s_mul_i32 s1, s1, s5
	s_branch .LBB11_1308

; #define LAS __attribute__((address_space(3)))
; DEVI int otid() { int t = threadIdx.x; asm volatile("" : "+v"(t)); return t; }
; DEVI void dsa_phase(LAS unsigned char* lds, const bf16_t* EV, const float* SC, bf16_t* O) {
;     const int tid = otid(), wid = tid >> 6, lane = tid & 63;
;     LAS u64* maskl = (LAS u64*)(lds + OFF_MASK);
;     for (int u = blockIdx.x; u < NB * 64; u += gridDim.x) {
;         const int g = 63 - (u & 63), b = u >> 6, t0 = 32 * g, m0 = b * SEQ + t0, c = g >> 1;
; #pragma unroll 1
;         for (int rr = 0; rr < 4; ++rr) { const int row = 4 * wid + rr; select_row(SC + (size_t)(m0 + row) * SEQ, c, maskl + row * 32, lane); }
;         asm volatile("s_waitcnt lgkmcnt(0)" ::: "memory"); __builtin_amdgcn_s_barrier(); asm volatile("" ::: "memory");
;         attn_unit<M_DSA>(lds, EV + (size_t)m0 * EVP + EV_QA + wid * HD, EVP, EV + (size_t)(b * SEQ) * EVP + EV_KA, EV + (size_t)(b * SEQ) * EVP + EV_VA, EVP,
;                          O + (size_t)m0 * DM + wid * HD, DM, 0, c + 1, 1, 0, 1 << 30, t0);
.LBB11_1358:
	v_readlane_b32 s1, v249, 40
	s_mov_b64 s[2:3], 0
	v_and_b32_e32 v1, 63, v0
	v_readlane_b32 s4, v251, 16
	v_readlane_b32 s5, v251, 17
	v_mov_b32_e32 v1, v0
	s_andn2_b64 vcc, exec, s[4:5]
	s_cbranch_vccnz .LBB11_1665
	v_readlane_b32 s4, v249, 17
	v_mov_b64_e32 v[4:5], s[2:3]
	v_readlane_b32 s18, v249, 31
	v_readlane_b32 s19, v249, 32
	s_mov_b64 s[2:3], 0x53200000
	v_and_b32_e32 v154, 63, v1
	v_lshl_add_u64 v[148:149], s[18:19], 0, v[4:5]
	v_lshl_add_u64 v[150:151], v[148:149], 0, s[2:3]
	s_mov_b64 s[2:3], 0x5ce00000
	v_ashrrev_i32_e32 v1, 6, v1
	v_lshl_add_u64 v[152:153], v[148:149], 0, s[2:3]
	v_cmp_ne_u32_e64 s[2:3], 0, v154
	v_lshlrev_b32_e32 v4, 7, v1
	v_ashrrev_i32_e32 v5, 31, v4
	v_writelane_b32 v252, s2, 27
	v_lshlrev_b64 v[4:5], 1, v[4:5]
	v_readlane_b32 s1, v255, 8
	v_writelane_b32 v252, s3, 28
	v_readlane_b32 s9, v249, 22
	v_lshl_add_u64 v[156:157], v[150:151], 0, v[4:5]
	v_lshl_add_u64 v[4:5], v[148:149], 0, v[4:5]
	s_mov_b64 s[2:3], 0x59200000
	v_writelane_b32 v252, s1, 29
	v_readlane_b32 s1, v251, 61
	v_lshlrev_b32_e32 v155, 2, v1
	v_cmp_eq_u32_e64 s[36:37], 0, v154
	v_lshl_add_u64 v[158:159], v[4:5], 0, s[2:3]
	v_lshlrev_b32_e32 v2, 2, v154
	v_readlane_b32 s9, v251, 59
	s_xor_b32 s9, s9, 0x7e0
	s_mov_b32 s3, s1
	v_readlane_b32 s5, v249, 18
	v_readlane_b32 s6, v249, 19
	v_readlane_b32 s7, v249, 20
	v_readlane_b32 s8, v249, 21
	v_readlane_b32 s10, v249, 23
	v_readlane_b32 s11, v249, 24
	v_readlane_b32 s12, v249, 25
	v_readlane_b32 s13, v249, 26
	v_readlane_b32 s14, v249, 27
	v_readlane_b32 s15, v249, 28
	v_readlane_b32 s16, v249, 29
	v_readlane_b32 s17, v249, 30
	s_branch .LBB11_1361

; #define STEP_BEGIN(idx, flag) if (lo <= (idx) && (idx) < hi) { for (int rep_ = 0; rep_ < (((REPEAT_MASK) & (flag)) ? 2 : 1); ++rep_) { if (prev) xcd_barrier(bar); prev = true; int lane = lane_k, wave = wave_k; size_t wz_ = 0; asm volatile("" : "+v"(lane), "+s"(wave), "+s"(wz_)); unsigned char* ws = ws_k + wz_;     const int gw = blockIdx.x * 8 + wave; (void)gw; (void)lane;
; template <class Epi, class Sched, bool ALIGN_EPI = false, bool SP2 = false>
; __device__ __forceinline__ void gemm_phase(PG8_LAS unsigned char* lds, const Gemm g, const Sched& S, const Epi& E) {
;     int tid_ = threadIdx.x; asm volatile("" : "+v"(tid_));
;     const int tid = tid_, wid = __builtin_amdgcn_readfirstlane(tid >> 6), lane = tid & 63, wr = wid >> 2, wc = wid & 3, fr = lane & 15, fq = lane >> 4;
;     const int K = g.K, nt = K / BK;
;     unsigned voffA[2], voffB[2];
; #pragma unroll
;     for (int i = 0; i < 2; ++i) { int R, C; stage_rc(tid * 16 + i * 8192, R, C); const int Rb = Epi::PERM ? ((R & ~31) + perm32(R & 31)) : R;
;         voffA[i] = (unsigned)(R * K + C) * 2u; voffB[i] = (unsigned)(Rb * K + C) * 2u; }
;     const size_t kstep = (size_t)(BK * 2);
;     const size_t hstep = (size_t)HALF * K * 2;
;     const size_t tstep = 2 * hstep;
;     const unsigned ldsw = (unsigned)wid * 1024u;
;     const int aoff = lds_byte(wr * 64 + fr, fq * 8), boff = lds_byte(wc * 32 + fr, fq * 8);
;     ...
;     Unit cur, nxt; int ui = 0;
;     if (!S.next(0, cur)) return;
; __global__ void __launch_bounds__(512, 2) k_mega(MegaArgs a) {
;     ...
;             STEP_BEGIN(base + 5, F_OUT) {
;                 unsigned* ctl = (unsigned*)(ws + WS_CTL);
;     ...
;                 pg8::EpiLnFused E{(sb == 0) ? a.in[0] : (const float*)nullptr, XB, (sb == 15) ? a.out : nullptr, DM, lng, lnb, ALPHA, ocs, st};
;                 run_gemm_fused(lds, oA, oB, MT, DM, oK, E);
.Lsp_out:
.LBB11_1880:
	v_readlane_b32 s4, v251, 16
	v_readlane_b32 s1, v249, 40
	s_mov_b64 s[2:3], 0
	v_and_b32_e32 v1, 63, v0
	s_waitcnt vmcnt(0)
	v_mov_b32_e32 v142, v0
	v_readlane_b32 s5, v251, 17
	s_andn2_b64 vcc, exec, s[4:5]
	v_readfirstlane_b32 s24, v142
	s_cbranch_vccz .LBB11_1881
	s_getpc_b64 s[98:99]

; #define LAS __attribute__((address_space(3)))
; __global__ void __launch_bounds__(512, 2) k_mega(MegaArgs a) {
;     extern __shared__ __attribute__((aligned(16))) unsigned char dyn_lds[];
;     LAS unsigned char* lds = (LAS unsigned char*)dyn_lds;
;     volatile LAS unsigned* MISC = (volatile LAS unsigned*)(lds + MISC_OFF);
;     const int tid = threadIdx.x, lane_k = tid & 63, wave_k = __builtin_amdgcn_readfirstlane(tid >> 6);
;     const int ngw = gridDim.x * 8;
	.amdhsa_kernel _Z6k_mega8MegaArgs
		.amdhsa_group_segment_fixed_size 0
		.amdhsa_private_segment_fixed_size 0
		.amdhsa_kernarg_size 392
		.amdhsa_user_sgpr_count 2
		.amdhsa_user_sgpr_dispatch_ptr 0
		.amdhsa_user_sgpr_queue_ptr 0
		.amdhsa_user_sgpr_kernarg_segment_ptr 1
		.amdhsa_user_sgpr_dispatch_id 0
		.amdhsa_user_sgpr_kernarg_preload_length 0
		.amdhsa_user_sgpr_kernarg_preload_offset 0
		.amdhsa_user_sgpr_private_segment_size 0
		.amdhsa_uses_dynamic_stack 0
		.amdhsa_enable_private_segment 0
		.amdhsa_system_sgpr_workgroup_id_x 1
		.amdhsa_system_sgpr_workgroup_id_y 0
		.amdhsa_system_sgpr_workgroup_id_z 0
		.amdhsa_system_sgpr_workgroup_info 0
		.amdhsa_system_vgpr_workitem_id 0
		.amdhsa_next_free_vgpr 256
		.amdhsa_next_free_sgpr 102
		.amdhsa_accum_offset 256
		.amdhsa_reserve_vcc 1
		.amdhsa_float_round_mode_32 0
		.amdhsa_float_round_mode_16_64 0
		.amdhsa_float_denorm_mode_32 3
		.amdhsa_float_denorm_mode_16_64 3
		.amdhsa_dx10_clamp 1
		.amdhsa_ieee_mode 1
		.amdhsa_fp16_overflow 0
		.amdhsa_tg_split 0
		.amdhsa_exception_fp_ieee_invalid_op 0
		.amdhsa_exception_fp_denorm_src 0
		.amdhsa_exception_fp_ieee_div_zero 0
		.amdhsa_exception_fp_ieee_overflow 0
		.amdhsa_exception_fp_ieee_underflow 0
		.amdhsa_exception_fp_ieee_inexact 0
		.amdhsa_exception_int_div_zero 0
	.end_amdhsa_kernel

; #define LAS __attribute__((address_space(3)))
; DEVI unsigned pk2(float lo, float hi) { return f2bf(lo) | (f2bf(hi) << 16); }
; __global__ __launch_bounds__(512) void k_convert(const float* W, int ldw, int nsrc, int K, bf16_t* WT, int ngroups, int mode) {
;     extern __shared__ __attribute__((aligned(16))) unsigned char dyn_lds[];
;     const int wave = threadIdx.x >> 6, lane = threadIdx.x & 63;
;     LAS float* scr = (LAS float*)((LAS unsigned char*)dyn_lds + wave * 8448);
;     convert_matrix(W, ldw, nsrc, K, WT, ngroups, mode, blockIdx.x * 8 + wave, gridDim.x * 8, scr, lane);
; }
; __global__ __launch_bounds__(256) void k_rope_tables(f32x2* t128, f32x2* t64) {
;     const int i = blockIdx.x * 256 + threadIdx.x;
;     if (i < SEQ * 96) {
;         const int pos = i / 96, f = i % 96; const bool big = f < 64; const int ff = big ? f : f - 64; const double half = big ? 64.0 : 32.0;
;         const double inv = exp2(-(double)ff / half * 13.287712379549449);
;         const double rev = (double)pos * inv * 0.15915494309189535; const double fr = rev - rint(rev);
;         const float c = __builtin_amdgcn_cosf((float)fr), s = __builtin_amdgcn_sinf((float)fr);
;         if (big) t128[pos * 64 + ff] = (f32x2){c, s}; else t64[pos * 32 + ff] = (f32x2){c, s};
;     }
; }
; __global__ __launch_bounds__(256) void k_cvt_x(const float* x, float* X, bf16_t* XB, size_t n4) {
;     for (size_t i = blockIdx.x * 256ull + threadIdx.x; i < n4; i += gridDim.x * 256ull) {
;         const f32x4 v = ((const f32x4*)x)[i]; if (X) ((f32x4*)X)[i] = v;
;         u32x2 o; o.x = pk2(v.x, v.y); o.y = pk2(v.z, v.w); ((u32x2*)XB)[i] = o; }
; }
amdhsa.kernels:
  - .agpr_count:     0
    .args:
      - .address_space:  global
        .offset:         0
        .size:           8
        .value_kind:     global_buffer
      - .offset:         8
        .size:           4
        .value_kind:     by_value
      - .offset:         12
        .size:           4
        .value_kind:     by_value
      - .offset:         16
        .size:           4
        .value_kind:     by_value
      - .address_space:  global
        .offset:         24
        .size:           8
        .value_kind:     global_buffer
      - .offset:         32
        .size:           4
        .value_kind:     by_value
      - .offset:         36
        .size:           4
        .value_kind:     by_value
      - .offset:         40
        .size:           4
        .value_kind:     hidden_block_count_x
      - .offset:         44
        .size:           4
        .value_kind:     hidden_block_count_y
      - .offset:         48
        .size:           4
        .value_kind:     hidden_block_count_z
      - .offset:         52
        .size:           2
        .value_kind:     hidden_group_size_x
      - .offset:         54
        .size:           2
        .value_kind:     hidden_group_size_y
      - .offset:         56
        .size:           2
        .value_kind:     hidden_group_size_z
      - .offset:         58
        .size:           2
        .value_kind:     hidden_remainder_x
      - .offset:         60
        .size:           2
        .value_kind:     hidden_remainder_y
      - .offset:         62
        .size:           2
        .value_kind:     hidden_remainder_z
      - .offset:         80
        .size:           8
        .value_kind:     hidden_global_offset_x
      - .offset:         88
        .size:           8
        .value_kind:     hidden_global_offset_y
      - .offset:         96
        .size:           8
        .value_kind:     hidden_global_offset_z
      - .offset:         104
        .size:           2
        .value_kind:     hidden_grid_dims
      - .offset:         160
        .size:           4
        .value_kind:     hidden_dynamic_lds_size
    .group_segment_fixed_size: 0
    .kernarg_segment_align: 8
    .kernarg_segment_size: 296
    .language:       OpenCL C
    .language_version:
      - 2
      - 0
    .max_flat_workgroup_size: 512
    .name:           _Z9k_convertPKfiiiPtii
    .private_segment_fixed_size: 0
    .sgpr_count:     103
    .sgpr_spill_count: 0
    .symbol:         _Z9k_convertPKfiiiPtii.kd
    .uniform_work_group_size: 1
    .uses_dynamic_stack: false
    .vgpr_count:     58
    .vgpr_spill_count: 0
    .wavefront_size: 64
  - .agpr_count:     0
    .args:
      - .address_space:  global
        .offset:         0
        .size:           8
        .value_kind:     global_buffer
      - .address_space:  global
        .offset:         8
        .size:           8
        .value_kind:     global_buffer
    .group_segment_fixed_size: 0
    .kernarg_segment_align: 8
    .kernarg_segment_size: 16
    .language:       OpenCL C
    .language_version:
      - 2
      - 0
    .max_flat_workgroup_size: 256
    .name:           _Z13k_rope_tablesPDv2_fS0_
    .private_segment_fixed_size: 0
    .sgpr_count:     14
    .sgpr_spill_count: 0
    .symbol:         _Z13k_rope_tablesPDv2_fS0_.kd
    .uniform_work_group_size: 1
    .uses_dynamic_stack: false
    .vgpr_count:     14
    .vgpr_spill_count: 0
    .wavefront_size: 64
  - .agpr_count:     0
    .args:
      - .address_space:  global
        .offset:         0
        .size:           8
        .value_kind:     global_buffer
      - .address_space:  global
        .offset:         8
        .size:           8
        .value_kind:     global_buffer
      - .address_space:  global
        .offset:         16
        .size:           8
        .value_kind:     global_buffer
      - .offset:         24
        .size:           8
        .value_kind:     by_value
      - .offset:         32
        .size:           4
        .value_kind:     hidden_block_count_x
      - .offset:         36
        .size:           4
        .value_kind:     hidden_block_count_y
      - .offset:         40
        .size:           4
        .value_kind:     hidden_block_count_z
      - .offset:         44
        .size:           2
        .value_kind:     hidden_group_size_x
      - .offset:         46
        .size:           2
        .value_kind:     hidden_group_size_y
      - .offset:         48
        .size:           2
        .value_kind:     hidden_group_size_z
      - .offset:         50
        .size:           2
        .value_kind:     hidden_remainder_x
      - .offset:         52
        .size:           2
        .value_kind:     hidden_remainder_y
      - .offset:         54
        .size:           2
        .value_kind:     hidden_remainder_z
      - .offset:         72
        .size:           8
        .value_kind:     hidden_global_offset_x
      - .offset:         80
        .size:           8
        .value_kind:     hidden_global_offset_y
      - .offset:         88
        .size:           8
        .value_kind:     hidden_global_offset_z
      - .offset:         96
        .size:           2
        .value_kind:     hidden_grid_dims
    .group_segment_fixed_size: 0
    .kernarg_segment_align: 8
    .kernarg_segment_size: 288
    .language:       OpenCL C
    .language_version:
      - 2
      - 0
    .max_flat_workgroup_size: 256
    .name:           _Z7k_cvt_xPKfPfPtm
    .private_segment_fixed_size: 0
    .sgpr_count:     26
    .sgpr_spill_count: 0
    .symbol:         _Z7k_cvt_xPKfPfPtm.kd
    .uniform_work_group_size: 1
    .uses_dynamic_stack: false
    .vgpr_count:     12
    .vgpr_spill_count: 0
    .wavefront_size: 64
; DEVI unsigned f2bf(float f) { unsigned u = __float_as_uint(f); return (u + 0x7fffu + ((u >> 16) & 1u)) >> 16; }
; __global__ __launch_bounds__(512) void k_gemm_naive(const bf16_t* A, int lda, const bf16_t* Bt, int ldb, float* C, int ldc, int M, int N, int K) {
;     const int gw = blockIdx.x * 8 + (threadIdx.x >> 6), ngw = gridDim.x * 8, lane = threadIdx.x & 63;
;     const int ntn = N / 16, ntm = M / 32;
;     for (int t = gw; t < ntm * ntn; t += ngw) {
;         const int tm = t / ntn, tn = t % ntn;
;         const bf16_t* a0 = A + (size_t)(tm * 32 + (lane & 15)) * lda + 8 * (lane >> 4);
;         const bf16_t* a1 = a0 + (size_t)16 * lda;
;         const bf16_t* b = Bt + (size_t)(tn * 16 + (lane & 15)) * ldb + 8 * (lane >> 4);
;         f32x4 c0 = {0.f, 0.f, 0.f, 0.f}, c1 = {0.f, 0.f, 0.f, 0.f};
; #pragma unroll 4
;         for (int k = 0; k < K; k += 32) {
;             const bf16x8 fa0 = *(const bf16x8*)(a0 + k), fa1 = *(const bf16x8*)(a1 + k), fb = *(const bf16x8*)(b + k);
;             c0 = __builtin_amdgcn_mfma_f32_16x16x32_bf16(fa0, fb, c0, 0, 0, 0);
;             c1 = __builtin_amdgcn_mfma_f32_16x16x32_bf16(fa1, fb, c1, 0, 0, 0);
;         }
; #pragma unroll
;         for (int r = 0; r < 4; ++r) {
;             C[(size_t)(tm * 32 + (lane >> 4) * 4 + r) * ldc + tn * 16 + (lane & 15)] = c0[r];
;             C[(size_t)(tm * 32 + 16 + (lane >> 4) * 4 + r) * ldc + tn * 16 + (lane & 15)] = c1[r];
;         }
;     }
; }
; __global__ __launch_bounds__(256) void k_swiglu(const float* C, bf16_t* H) {
;     for (size_t i = blockIdx.x * 256ull + threadIdx.x; i < (size_t)MT * FFN; i += gridDim.x * 256ull) {
;         const size_t m = i / FFN, j = i % FFN; const float a = C[m * 2 * FFN + j], g = C[m * 2 * FFN + FFN + j];
;         H[i] = (bf16_t)f2bf(a / (1.f + expf(-a)) * g); }
; }
  - .agpr_count:     0
    .args:
      - .address_space:  global
        .offset:         0
        .size:           8
        .value_kind:     global_buffer
      - .offset:         8
        .size:           4
        .value_kind:     by_value
      - .address_space:  global
        .offset:         16
        .size:           8
        .value_kind:     global_buffer
      - .offset:         24
        .size:           4
        .value_kind:     by_value
      - .address_space:  global
        .offset:         32
        .size:           8
        .value_kind:     global_buffer
      - .offset:         40
        .size:           4
        .value_kind:     by_value
      - .offset:         44
        .size:           4
        .value_kind:     by_value
      - .offset:         48
        .size:           4
        .value_kind:     by_value
      - .offset:         52
        .size:           4
        .value_kind:     by_value
      - .offset:         56
        .size:           4
        .value_kind:     hidden_block_count_x
      - .offset:         60
        .size:           4
        .value_kind:     hidden_block_count_y
      - .offset:         64
        .size:           4
        .value_kind:     hidden_block_count_z
      - .offset:         68
        .size:           2
        .value_kind:     hidden_group_size_x
      - .offset:         70
        .size:           2
        .value_kind:     hidden_group_size_y
      - .offset:         72
        .size:           2
        .value_kind:     hidden_group_size_z
      - .offset:         74
        .size:           2
        .value_kind:     hidden_remainder_x
      - .offset:         76
        .size:           2
        .value_kind:     hidden_remainder_y
      - .offset:         78
        .size:           2
        .value_kind:     hidden_remainder_z
      - .offset:         96
        .size:           8
        .value_kind:     hidden_global_offset_x
      - .offset:         104
        .size:           8
        .value_kind:     hidden_global_offset_y
      - .offset:         112
        .size:           8
        .value_kind:     hidden_global_offset_z
      - .offset:         120
        .size:           2
        .value_kind:     hidden_grid_dims
    .group_segment_fixed_size: 0
    .kernarg_segment_align: 8
    .kernarg_segment_size: 312
    .language:       OpenCL C
    .language_version:
      - 2
      - 0
    .max_flat_workgroup_size: 512
    .name:           _Z12k_gemm_naivePKtiS0_iPfiiii
    .private_segment_fixed_size: 0
    .sgpr_count:     26
    .sgpr_spill_count: 0
    .symbol:         _Z12k_gemm_naivePKtiS0_iPfiiii.kd
    .uniform_work_group_size: 1
    .uses_dynamic_stack: false
    .vgpr_count:     34
    .vgpr_spill_count: 0
    .wavefront_size: 64
  - .agpr_count:     0
    .args:
      - .address_space:  global
        .offset:         0
        .size:           8
        .value_kind:     global_buffer
      - .address_space:  global
        .offset:         8
        .size:           8
        .value_kind:     global_buffer
      - .offset:         16
        .size:           4
        .value_kind:     hidden_block_count_x
      - .offset:         20
        .size:           4
        .value_kind:     hidden_block_count_y
      - .offset:         24
        .size:           4
        .value_kind:     hidden_block_count_z
      - .offset:         28
        .size:           2
        .value_kind:     hidden_group_size_x
      - .offset:         30
        .size:           2
        .value_kind:     hidden_group_size_y
      - .offset:         32
        .size:           2
        .value_kind:     hidden_group_size_z
      - .offset:         34
        .size:           2
        .value_kind:     hidden_remainder_x
      - .offset:         36
        .size:           2
        .value_kind:     hidden_remainder_y
      - .offset:         38
        .size:           2
        .value_kind:     hidden_remainder_z
      - .offset:         56
        .size:           8
        .value_kind:     hidden_global_offset_x
      - .offset:         64
        .size:           8
        .value_kind:     hidden_global_offset_y
      - .offset:         72
        .size:           8
        .value_kind:     hidden_global_offset_z
      - .offset:         80
        .size:           2
        .value_kind:     hidden_grid_dims
    .group_segment_fixed_size: 0
    .kernarg_segment_align: 8
    .kernarg_segment_size: 272
    .language:       OpenCL C
    .language_version:
      - 2
      - 0
    .max_flat_workgroup_size: 256
    .name:           _Z8k_swigluPKfPt
    .private_segment_fixed_size: 0
    .sgpr_count:     32
    .sgpr_spill_count: 0
    .symbol:         _Z8k_swigluPKfPt.kd
    .uniform_work_group_size: 1
    .uses_dynamic_stack: false
    .vgpr_count:     35
    .vgpr_spill_count: 0
    .wavefront_size: 64
; DEVI unsigned f2bf(float f) { unsigned u = __float_as_uint(f); return (u + 0x7fffu + ((u >> 16) & 1u)) >> 16; }
; __global__ __launch_bounds__(256) void k_resid(const float* C, const float* X, float* Y, float cscale) {
;     for (size_t i = blockIdx.x * 256ull + threadIdx.x; i < (size_t)MT * DM; i += gridDim.x * 256ull) Y[i] = ALPHA * X[i] + cscale * C[i];
; }
; __global__ __launch_bounds__(256) void k_tobf(const float* C, bf16_t* O, size_t n) {
;     for (size_t i = blockIdx.x * 256ull + threadIdx.x; i < n; i += gridDim.x * 256ull) O[i] = (bf16_t)f2bf(C[i]);
; }
  - .agpr_count:     0
    .args:
      - .address_space:  global
        .offset:         0
        .size:           8
        .value_kind:     global_buffer
      - .address_space:  global
        .offset:         8
        .size:           8
        .value_kind:     global_buffer
      - .address_space:  global
        .offset:         16
        .size:           8
        .value_kind:     global_buffer
      - .offset:         24
        .size:           4
        .value_kind:     by_value
      - .offset:         32
        .size:           4
        .value_kind:     hidden_block_count_x
      - .offset:         36
        .size:           4
        .value_kind:     hidden_block_count_y
      - .offset:         40
        .size:           4
        .value_kind:     hidden_block_count_z
      - .offset:         44
        .size:           2
        .value_kind:     hidden_group_size_x
      - .offset:         46
        .size:           2
        .value_kind:     hidden_group_size_y
      - .offset:         48
        .size:           2
        .value_kind:     hidden_group_size_z
      - .offset:         50
        .size:           2
        .value_kind:     hidden_remainder_x
      - .offset:         52
        .size:           2
        .value_kind:     hidden_remainder_y
      - .offset:         54
        .size:           2
        .value_kind:     hidden_remainder_z
      - .offset:         72
        .size:           8
        .value_kind:     hidden_global_offset_x
      - .offset:         80
        .size:           8
        .value_kind:     hidden_global_offset_y
      - .offset:         88
        .size:           8
        .value_kind:     hidden_global_offset_z
      - .offset:         96
        .size:           2
        .value_kind:     hidden_grid_dims
    .group_segment_fixed_size: 0
    .kernarg_segment_align: 8
    .kernarg_segment_size: 288
    .language:       OpenCL C
    .language_version:
      - 2
      - 0
    .max_flat_workgroup_size: 256
    .name:           _Z7k_residPKfS0_Pff
    .private_segment_fixed_size: 0
    .sgpr_count:     22
    .sgpr_spill_count: 0
    .symbol:         _Z7k_residPKfS0_Pff.kd
    .uniform_work_group_size: 1
    .uses_dynamic_stack: false
    .vgpr_count:     10
    .vgpr_spill_count: 0
    .wavefront_size: 64
  - .agpr_count:     0
    .args:
      - .address_space:  global
        .offset:         0
        .size:           8
        .value_kind:     global_buffer
      - .address_space:  global
        .offset:         8
        .size:           8
        .value_kind:     global_buffer
      - .offset:         16
        .size:           8
        .value_kind:     by_value
      - .offset:         24
        .size:           4
        .value_kind:     hidden_block_count_x
      - .offset:         28
        .size:           4
        .value_kind:     hidden_block_count_y
      - .offset:         32
        .size:           4
        .value_kind:     hidden_block_count_z
      - .offset:         36
        .size:           2
        .value_kind:     hidden_group_size_x
      - .offset:         38
        .size:           2
        .value_kind:     hidden_group_size_y
      - .offset:         40
        .size:           2
        .value_kind:     hidden_group_size_z
      - .offset:         42
        .size:           2
        .value_kind:     hidden_remainder_x
      - .offset:         44
        .size:           2
        .value_kind:     hidden_remainder_y
      - .offset:         46
        .size:           2
        .value_kind:     hidden_remainder_z
      - .offset:         64
        .size:           8
        .value_kind:     hidden_global_offset_x
      - .offset:         72
        .size:           8
        .value_kind:     hidden_global_offset_y
      - .offset:         80
        .size:           8
        .value_kind:     hidden_global_offset_z
      - .offset:         88
        .size:           2
        .value_kind:     hidden_grid_dims
    .group_segment_fixed_size: 0
    .kernarg_segment_align: 8
    .kernarg_segment_size: 280
    .language:       OpenCL C
    .language_version:
      - 2
      - 0
    .max_flat_workgroup_size: 256
    .name:           _Z6k_tobfPKfPtm
    .private_segment_fixed_size: 0
    .sgpr_count:     20
    .sgpr_spill_count: 0
    .symbol:         _Z6k_tobfPKfPtm.kd
    .uniform_work_group_size: 1
    .uses_dynamic_stack: false
    .vgpr_count:     8
    .vgpr_spill_count: 0
    .wavefront_size: 64
; DEVI unsigned f2bf(float f) { unsigned u = __float_as_uint(f); return (u + 0x7fffu + ((u >> 16) & 1u)) >> 16; }
; __global__ __launch_bounds__(512) void k_ln(const float* Y, const float* g, const float* b, float* X, bf16_t* XB, float* OUT) {
;     const int gw = blockIdx.x * 8 + (threadIdx.x >> 6), ngw = gridDim.x * 8, lane = threadIdx.x & 63;
;     for (int m = gw; m < MT; m += ngw) ln_row(Y + (size_t)m * DM, g, b, X + (size_t)m * DM, XB + (size_t)m * DM, OUT ? OUT + (size_t)m * DM : nullptr, lane);
; }
; __global__ __launch_bounds__(256) void k_even_split(const float* C, bf16_t* EV, const f32x2* t128, const f32x2* t64) {
;     for (size_t i = blockIdx.x * 256ull + threadIdx.x; i < (size_t)MT * EVP; i += gridDim.x * 256ull) {
;         const int m = (int)(i / EVP), dcol = (int)(i % EVP), pos = m % SEQ; const float* c = C + (size_t)m * EVEN_COLS;
;         float v = 0.f;
;         if (dcol < 2384) {
;             const int s = dcol;
;             if (s < 1152) {
;                 const int d = s & 127;
;                 if (d < 64) { const f32x2 cs = t128[pos * 64 + d]; v = c[s] * cs.x - c[s + 64] * cs.y; }
;                 else { const f32x2 cs = t128[pos * 64 + d - 64]; v = c[s] * cs.x + c[s - 64] * cs.y; }
;             } else if (s < 1280) v = c[s];
;             else if (s < 2368) {
;                 const int d = (s - 1280) & 63;
;                 if (d < 32) { const f32x2 cs = t64[pos * 32 + d]; v = c[s] * cs.x - c[s + 32] * cs.y; }
;                 else { const f32x2 cs = t64[pos * 32 + d - 32]; v = c[s] * cs.x + c[s - 32] * cs.y; }
;             } else v = c[s];
;         } else if (dcol >= 2560) v = c[dcol - 176];
;         EV[i] = (bf16_t)f2bf(v);
;     }
; }
  - .agpr_count:     0
    .args:
      - .address_space:  global
        .offset:         0
        .size:           8
        .value_kind:     global_buffer
      - .address_space:  global
        .offset:         8
        .size:           8
        .value_kind:     global_buffer
      - .address_space:  global
        .offset:         16
        .size:           8
        .value_kind:     global_buffer
      - .address_space:  global
        .offset:         24
        .size:           8
        .value_kind:     global_buffer
      - .address_space:  global
        .offset:         32
        .size:           8
        .value_kind:     global_buffer
      - .address_space:  global
        .offset:         40
        .size:           8
        .value_kind:     global_buffer
      - .offset:         48
        .size:           4
        .value_kind:     hidden_block_count_x
      - .offset:         52
        .size:           4
        .value_kind:     hidden_block_count_y
      - .offset:         56
        .size:           4
        .value_kind:     hidden_block_count_z
      - .offset:         60
        .size:           2
        .value_kind:     hidden_group_size_x
      - .offset:         62
        .size:           2
        .value_kind:     hidden_group_size_y
      - .offset:         64
        .size:           2
        .value_kind:     hidden_group_size_z
      - .offset:         66
        .size:           2
        .value_kind:     hidden_remainder_x
      - .offset:         68
        .size:           2
        .value_kind:     hidden_remainder_y
      - .offset:         70
        .size:           2
        .value_kind:     hidden_remainder_z
      - .offset:         88
        .size:           8
        .value_kind:     hidden_global_offset_x
      - .offset:         96
        .size:           8
        .value_kind:     hidden_global_offset_y
      - .offset:         104
        .size:           8
        .value_kind:     hidden_global_offset_z
      - .offset:         112
        .size:           2
        .value_kind:     hidden_grid_dims
    .group_segment_fixed_size: 0
    .kernarg_segment_align: 8
    .kernarg_segment_size: 304
    .language:       OpenCL C
    .language_version:
      - 2
      - 0
    .max_flat_workgroup_size: 512
    .name:           _Z4k_lnPKfS0_S0_PfPtS1_
    .private_segment_fixed_size: 0
    .sgpr_count:     26
    .sgpr_spill_count: 0
    .symbol:         _Z4k_lnPKfS0_S0_PfPtS1_.kd
    .uniform_work_group_size: 1
    .uses_dynamic_stack: false
    .vgpr_count:     108
    .vgpr_spill_count: 0
    .wavefront_size: 64
  - .agpr_count:     0
    .args:
      - .address_space:  global
        .offset:         0
        .size:           8
        .value_kind:     global_buffer
      - .address_space:  global
        .offset:         8
        .size:           8
        .value_kind:     global_buffer
      - .address_space:  global
        .offset:         16
        .size:           8
        .value_kind:     global_buffer
      - .address_space:  global
        .offset:         24
        .size:           8
        .value_kind:     global_buffer
      - .offset:         32
        .size:           4
        .value_kind:     hidden_block_count_x
      - .offset:         36
        .size:           4
        .value_kind:     hidden_block_count_y
      - .offset:         40
        .size:           4
        .value_kind:     hidden_block_count_z
      - .offset:         44
        .size:           2
        .value_kind:     hidden_group_size_x
      - .offset:         46
        .size:           2
        .value_kind:     hidden_group_size_y
      - .offset:         48
        .size:           2
        .value_kind:     hidden_group_size_z
      - .offset:         50
        .size:           2
        .value_kind:     hidden_remainder_x
      - .offset:         52
        .size:           2
        .value_kind:     hidden_remainder_y
      - .offset:         54
        .size:           2
        .value_kind:     hidden_remainder_z
      - .offset:         72
        .size:           8
        .value_kind:     hidden_global_offset_x
      - .offset:         80
        .size:           8
        .value_kind:     hidden_global_offset_y
      - .offset:         88
        .size:           8
        .value_kind:     hidden_global_offset_z
      - .offset:         96
        .size:           2
        .value_kind:     hidden_grid_dims
    .group_segment_fixed_size: 0
    .kernarg_segment_align: 8
    .kernarg_segment_size: 288
    .language:       OpenCL C
    .language_version:
      - 2
      - 0
    .max_flat_workgroup_size: 256
    .name:           _Z12k_even_splitPKfPtPKDv2_fS4_
    .private_segment_fixed_size: 0
    .sgpr_count:     37
    .sgpr_spill_count: 0
    .symbol:         _Z12k_even_splitPKfPtPKDv2_fS4_.kd
    .uniform_work_group_size: 1
    .uses_dynamic_stack: false
    .vgpr_count:     14
    .vgpr_spill_count: 0
    .wavefront_size: 64
; #define LAS __attribute__((address_space(3)))
; __global__ __launch_bounds__(512) void k_indexer_naive(const bf16_t* EV, float* SC) {
;     extern __shared__ __attribute__((aligned(16))) unsigned char dyn_lds[];
;     const int wave = threadIdx.x >> 6, lane = threadIdx.x & 63;
;     indexer_naive_phase(EV, SC, (LAS unsigned char*)dyn_lds, wave, lane, blockIdx.x * 8 + wave, gridDim.x * 8);
; }
; __global__ __launch_bounds__(512) void k_select(const float* SC, u64* MASK) {
;     const int gw = blockIdx.x * 8 + (threadIdx.x >> 6), ngw = gridDim.x * 8, lane = threadIdx.x & 63;
;     for (int m = gw; m < MT; m += ngw) select_row(SC + (size_t)m * SEQ, (m % SEQ) / 64, MASK + (size_t)m * 32, lane);
; }
  - .agpr_count:     0
    .args:
      - .address_space:  global
        .offset:         0
        .size:           8
        .value_kind:     global_buffer
      - .address_space:  global
        .offset:         8
        .size:           8
        .value_kind:     global_buffer
      - .offset:         16
        .size:           4
        .value_kind:     hidden_block_count_x
      - .offset:         20
        .size:           4
        .value_kind:     hidden_block_count_y
      - .offset:         24
        .size:           4
        .value_kind:     hidden_block_count_z
      - .offset:         28
        .size:           2
        .value_kind:     hidden_group_size_x
      - .offset:         30
        .size:           2
        .value_kind:     hidden_group_size_y
      - .offset:         32
        .size:           2
        .value_kind:     hidden_group_size_z
      - .offset:         34
        .size:           2
        .value_kind:     hidden_remainder_x
      - .offset:         36
        .size:           2
        .value_kind:     hidden_remainder_y
      - .offset:         38
        .size:           2
        .value_kind:     hidden_remainder_z
      - .offset:         56
        .size:           8
        .value_kind:     hidden_global_offset_x
      - .offset:         64
        .size:           8
        .value_kind:     hidden_global_offset_y
      - .offset:         72
        .size:           8
        .value_kind:     hidden_global_offset_z
      - .offset:         80
        .size:           2
        .value_kind:     hidden_grid_dims
      - .offset:         136
        .size:           4
        .value_kind:     hidden_dynamic_lds_size
    .group_segment_fixed_size: 0
    .kernarg_segment_align: 8
    .kernarg_segment_size: 272
    .language:       OpenCL C
    .language_version:
      - 2
      - 0
    .max_flat_workgroup_size: 512
    .name:           _Z15k_indexer_naivePKtPf
    .private_segment_fixed_size: 0
    .sgpr_count:     24
    .sgpr_spill_count: 0
    .symbol:         _Z15k_indexer_naivePKtPf.kd
    .uniform_work_group_size: 1
    .uses_dynamic_stack: false
    .vgpr_count:     163
    .vgpr_spill_count: 0
    .wavefront_size: 64
  - .agpr_count:     0
    .args:
      - .address_space:  global
        .offset:         0
        .size:           8
        .value_kind:     global_buffer
      - .address_space:  global
        .offset:         8
        .size:           8
        .value_kind:     global_buffer
      - .offset:         16
        .size:           4
        .value_kind:     hidden_block_count_x
      - .offset:         20
        .size:           4
        .value_kind:     hidden_block_count_y
      - .offset:         24
        .size:           4
        .value_kind:     hidden_block_count_z
      - .offset:         28
        .size:           2
        .value_kind:     hidden_group_size_x
      - .offset:         30
        .size:           2
        .value_kind:     hidden_group_size_y
      - .offset:         32
        .size:           2
        .value_kind:     hidden_group_size_z
      - .offset:         34
        .size:           2
        .value_kind:     hidden_remainder_x
      - .offset:         36
        .size:           2
        .value_kind:     hidden_remainder_y
      - .offset:         38
        .size:           2
        .value_kind:     hidden_remainder_z
      - .offset:         56
        .size:           8
        .value_kind:     hidden_global_offset_x
      - .offset:         64
        .size:           8
        .value_kind:     hidden_global_offset_y
      - .offset:         72
        .size:           8
        .value_kind:     hidden_global_offset_z
      - .offset:         80
        .size:           2
        .value_kind:     hidden_grid_dims
    .group_segment_fixed_size: 0
    .kernarg_segment_align: 8
    .kernarg_segment_size: 272
    .language:       OpenCL C
    .language_version:
      - 2
      - 0
    .max_flat_workgroup_size: 512
    .name:           _Z8k_selectPKfPy
    .private_segment_fixed_size: 0
    .sgpr_count:     106
    .sgpr_spill_count: 116
    .symbol:         _Z8k_selectPKfPy.kd
    .uniform_work_group_size: 1
    .uses_dynamic_stack: false
    .vgpr_count:     92
    .vgpr_spill_count: 0
    .wavefront_size: 64
  - .agpr_count:     0
    .args:
      - .offset:         0
        .size:           136
        .value_kind:     by_value
      - .offset:         136
        .size:           4
        .value_kind:     hidden_block_count_x
      - .offset:         140
        .size:           4
        .value_kind:     hidden_block_count_y
      - .offset:         144
        .size:           4
        .value_kind:     hidden_block_count_z
      - .offset:         148
        .size:           2
        .value_kind:     hidden_group_size_x
      - .offset:         150
        .size:           2
        .value_kind:     hidden_group_size_y
      - .offset:         152
        .size:           2
        .value_kind:     hidden_group_size_z
      - .offset:         154
        .size:           2
        .value_kind:     hidden_remainder_x
      - .offset:         156
        .size:           2
        .value_kind:     hidden_remainder_y
      - .offset:         158
        .size:           2
        .value_kind:     hidden_remainder_z
      - .offset:         176
        .size:           8
        .value_kind:     hidden_global_offset_x
      - .offset:         184
        .size:           8
        .value_kind:     hidden_global_offset_y
      - .offset:         192
        .size:           8
        .value_kind:     hidden_global_offset_z
      - .offset:         200
        .size:           2
        .value_kind:     hidden_grid_dims
      - .offset:         256
        .size:           4
        .value_kind:     hidden_dynamic_lds_size
    .group_segment_fixed_size: 0
    .kernarg_segment_align: 8
    .kernarg_segment_size: 392
    .language:       OpenCL C
    .language_version:
      - 2
      - 0
    .max_flat_workgroup_size: 512
    .name:           _Z6k_mega8MegaArgs
    .private_segment_fixed_size: 0
    .sgpr_count:     108
    .sgpr_spill_count: 421
    .symbol:         _Z6k_mega8MegaArgs.kd
    .uniform_work_group_size: 1
    .uses_dynamic_stack: false
    .vgpr_count:     256
    .vgpr_spill_count: 0
    .wavefront_size: 64
; #define LAS __attribute__((address_space(3)))
; template <int MODE> __global__ __launch_bounds__(512) void k_attn_naive(AttnArgs a) {
;     extern __shared__ __attribute__((aligned(16))) unsigned char dyn_lds[];
;     const int wave = threadIdx.x >> 6, lane = threadIdx.x & 63;
;     attn_naive_phase<MODE>(a, (LAS unsigned char*)dyn_lds, wave, lane, blockIdx.x * 8 + wave, gridDim.x * 8);
; }
  - .agpr_count:     0
    .args:
      - .offset:         0
        .size:           88
        .value_kind:     by_value
      - .offset:         88
        .size:           4
        .value_kind:     hidden_block_count_x
      - .offset:         92
        .size:           4
        .value_kind:     hidden_block_count_y
      - .offset:         96
        .size:           4
        .value_kind:     hidden_block_count_z
      - .offset:         100
        .size:           2
        .value_kind:     hidden_group_size_x
      - .offset:         102
        .size:           2
        .value_kind:     hidden_group_size_y
      - .offset:         104
        .size:           2
        .value_kind:     hidden_group_size_z
      - .offset:         106
        .size:           2
        .value_kind:     hidden_remainder_x
      - .offset:         108
        .size:           2
        .value_kind:     hidden_remainder_y
      - .offset:         110
        .size:           2
        .value_kind:     hidden_remainder_z
      - .offset:         128
        .size:           8
        .value_kind:     hidden_global_offset_x
      - .offset:         136
        .size:           8
        .value_kind:     hidden_global_offset_y
      - .offset:         144
        .size:           8
        .value_kind:     hidden_global_offset_z
      - .offset:         152
        .size:           2
        .value_kind:     hidden_grid_dims
      - .offset:         208
        .size:           4
        .value_kind:     hidden_dynamic_lds_size
    .group_segment_fixed_size: 0
    .kernarg_segment_align: 8
    .kernarg_segment_size: 344
    .language:       OpenCL C
    .language_version:
      - 2
      - 0
    .max_flat_workgroup_size: 512
    .name:           _Z12k_attn_naiveILi0EEv8AttnArgs
    .private_segment_fixed_size: 0
    .sgpr_count:     46
    .sgpr_spill_count: 0
    .symbol:         _Z12k_attn_naiveILi0EEv8AttnArgs.kd
    .uniform_work_group_size: 1
    .uses_dynamic_stack: false
    .vgpr_count:     40
    .vgpr_spill_count: 0
    .wavefront_size: 64
  - .agpr_count:     0
    .args:
      - .offset:         0
        .size:           88
        .value_kind:     by_value
      - .offset:         88
        .size:           4
        .value_kind:     hidden_block_count_x
      - .offset:         92
        .size:           4
        .value_kind:     hidden_block_count_y
      - .offset:         96
        .size:           4
        .value_kind:     hidden_block_count_z
      - .offset:         100
        .size:           2
        .value_kind:     hidden_group_size_x
      - .offset:         102
        .size:           2
        .value_kind:     hidden_group_size_y
      - .offset:         104
        .size:           2
        .value_kind:     hidden_group_size_z
      - .offset:         106
        .size:           2
        .value_kind:     hidden_remainder_x
      - .offset:         108
        .size:           2
        .value_kind:     hidden_remainder_y
      - .offset:         110
        .size:           2
        .value_kind:     hidden_remainder_z
      - .offset:         128
        .size:           8
        .value_kind:     hidden_global_offset_x
      - .offset:         136
        .size:           8
        .value_kind:     hidden_global_offset_y
      - .offset:         144
        .size:           8
        .value_kind:     hidden_global_offset_z
      - .offset:         152
        .size:           2
        .value_kind:     hidden_grid_dims
      - .offset:         208
        .size:           4
        .value_kind:     hidden_dynamic_lds_size
    .group_segment_fixed_size: 0
    .kernarg_segment_align: 8
    .kernarg_segment_size: 344
    .language:       OpenCL C
    .language_version:
      - 2
      - 0
    .max_flat_workgroup_size: 512
    .name:           _Z12k_attn_naiveILi1EEv8AttnArgs
    .private_segment_fixed_size: 0
    .sgpr_count:     66
    .sgpr_spill_count: 0
    .symbol:         _Z12k_attn_naiveILi1EEv8AttnArgs.kd
    .uniform_work_group_size: 1
    .uses_dynamic_stack: false
    .vgpr_count:     58
    .vgpr_spill_count: 0
    .wavefront_size: 64
; #define LAS __attribute__((address_space(3)))
; template <int MODE> __global__ __launch_bounds__(512) void k_attn_naive(AttnArgs a) {
;     extern __shared__ __attribute__((aligned(16))) unsigned char dyn_lds[];
;     const int wave = threadIdx.x >> 6, lane = threadIdx.x & 63;
;     attn_naive_phase<MODE>(a, (LAS unsigned char*)dyn_lds, wave, lane, blockIdx.x * 8 + wave, gridDim.x * 8);
; }
  - .agpr_count:     0
    .args:
      - .offset:         0
        .size:           88
        .value_kind:     by_value
      - .offset:         88
        .size:           4
        .value_kind:     hidden_block_count_x
      - .offset:         92
        .size:           4
        .value_kind:     hidden_block_count_y
      - .offset:         96
        .size:           4
        .value_kind:     hidden_block_count_z
      - .offset:         100
        .size:           2
        .value_kind:     hidden_group_size_x
      - .offset:         102
        .size:           2
        .value_kind:     hidden_group_size_y
      - .offset:         104
        .size:           2
        .value_kind:     hidden_group_size_z
      - .offset:         106
        .size:           2
        .value_kind:     hidden_remainder_x
      - .offset:         108
        .size:           2
        .value_kind:     hidden_remainder_y
      - .offset:         110
        .size:           2
        .value_kind:     hidden_remainder_z
      - .offset:         128
        .size:           8
        .value_kind:     hidden_global_offset_x
      - .offset:         136
        .size:           8
        .value_kind:     hidden_global_offset_y
      - .offset:         144
        .size:           8
        .value_kind:     hidden_global_offset_z
      - .offset:         152
        .size:           2
        .value_kind:     hidden_grid_dims
      - .offset:         208
        .size:           4
        .value_kind:     hidden_dynamic_lds_size
    .group_segment_fixed_size: 0
    .kernarg_segment_align: 8
    .kernarg_segment_size: 344
    .language:       OpenCL C
    .language_version:
      - 2
      - 0
    .max_flat_workgroup_size: 512
    .name:           _Z12k_attn_naiveILi2EEv8AttnArgs
    .private_segment_fixed_size: 0
    .sgpr_count:     56
    .sgpr_spill_count: 0
    .symbol:         _Z12k_attn_naiveILi2EEv8AttnArgs.kd
    .uniform_work_group_size: 1
    .uses_dynamic_stack: false
    .vgpr_count:     44
    .vgpr_spill_count: 0
    .wavefront_size: 64
  - .agpr_count:     0
    .args:
      - .offset:         0
        .size:           88
        .value_kind:     by_value
      - .offset:         88
        .size:           4
        .value_kind:     hidden_block_count_x
      - .offset:         92
        .size:           4
        .value_kind:     hidden_block_count_y
      - .offset:         96
        .size:           4
        .value_kind:     hidden_block_count_z
      - .offset:         100
        .size:           2
        .value_kind:     hidden_group_size_x
      - .offset:         102
        .size:           2
        .value_kind:     hidden_group_size_y
      - .offset:         104
        .size:           2
        .value_kind:     hidden_group_size_z
      - .offset:         106
        .size:           2
        .value_kind:     hidden_remainder_x
      - .offset:         108
        .size:           2
        .value_kind:     hidden_remainder_y
      - .offset:         110
        .size:           2
        .value_kind:     hidden_remainder_z
      - .offset:         128
        .size:           8
        .value_kind:     hidden_global_offset_x
      - .offset:         136
        .size:           8
        .value_kind:     hidden_global_offset_y
      - .offset:         144
        .size:           8
        .value_kind:     hidden_global_offset_z
      - .offset:         152
        .size:           2
        .value_kind:     hidden_grid_dims
      - .offset:         208
        .size:           4
        .value_kind:     hidden_dynamic_lds_size
    .group_segment_fixed_size: 0
    .kernarg_segment_align: 8
    .kernarg_segment_size: 344
    .language:       OpenCL C
    .language_version:
      - 2
      - 0
    .max_flat_workgroup_size: 512
    .name:           _Z12k_attn_naiveILi3EEv8AttnArgs
    .private_segment_fixed_size: 0
    .sgpr_count:     56
    .sgpr_spill_count: 0
    .symbol:         _Z12k_attn_naiveILi3EEv8AttnArgs.kd
    .uniform_work_group_size: 1
    .uses_dynamic_stack: false
    .vgpr_count:     56
    .vgpr_spill_count: 0
    .wavefront_size: 64
